# gate-chunk prefetch loads paired into dwordx4 + v_permlane32_swap (MLA latent, MLA context, NA epilogues); MLA context Wv^T loads halved like the latent ones
# speedup vs baseline: 1.0438x; 1.0196x over previous
.LBB0_502:
	s_or_b64 exec, exec, s[16:17]
	v_permlane32_swap_b32_e32 v210, v212
	v_permlane32_swap_b32_e32 v211, v213
	v_permlane32_swap_b32_e32 v214, v216
	v_permlane32_swap_b32_e32 v215, v217
	v_permlane32_swap_b32_e32 v218, v220
	v_permlane32_swap_b32_e32 v219, v221
	v_permlane32_swap_b32_e32 v222, v224
	v_permlane32_swap_b32_e32 v223, v225
	v_permlane32_swap_b32_e32 v226, v228
	v_permlane32_swap_b32_e32 v227, v229
	v_permlane32_swap_b32_e32 v230, v232
	v_permlane32_swap_b32_e32 v231, v233
	v_permlane32_swap_b32_e32 v234, v236
	v_permlane32_swap_b32_e32 v235, v237
	v_add_f32_e32 v64, v64, v65
	v_fmac_f32_e32 v64, v186, v96
	v_rcp_f32_e32 v67, v64
	s_lshl_b64 s[14:15], s[14:15], 12
	s_add_u32 s14, s23, s14
	s_addc_u32 s15, s24, s15
	v_mul_f32_e32 v16, v67, v16
	v_mul_f32_e32 v17, v67, v17
	v_cvt_pk_bf16_f32 v80, v16, v17
	v_mul_f32_e32 v16, v67, v18
	v_mul_f32_e32 v17, v67, v19
	v_cvt_pk_bf16_f32 v81, v16, v17
	v_mul_f32_e32 v16, v67, v20
	v_mul_f32_e32 v17, v67, v21
	v_cvt_pk_bf16_f32 v82, v16, v17
	v_mul_f32_e32 v16, v67, v22
	v_mul_f32_e32 v17, v67, v23
	v_cvt_pk_bf16_f32 v83, v16, v17
	v_mul_f32_e32 v16, v67, v24
	v_mul_f32_e32 v17, v67, v25
	v_cvt_pk_bf16_f32 v84, v16, v17
	v_mul_f32_e32 v16, v67, v26
	v_mul_f32_e32 v17, v67, v27
	v_cvt_pk_bf16_f32 v85, v16, v17
	v_mul_f32_e32 v16, v67, v28
	v_mul_f32_e32 v17, v67, v29
	v_cvt_pk_bf16_f32 v86, v16, v17
	v_mul_f32_e32 v16, v67, v30
	v_mul_f32_e32 v17, v67, v31
	v_cvt_pk_bf16_f32 v87, v16, v17
	v_mul_f32_e32 v16, v67, v32
	v_mul_f32_e32 v17, v67, v33
	v_cvt_pk_bf16_f32 v88, v16, v17
	v_mul_f32_e32 v16, v67, v34
	v_mul_f32_e32 v17, v67, v35
	v_cvt_pk_bf16_f32 v89, v16, v17
	v_mul_f32_e32 v16, v67, v36
	v_mul_f32_e32 v17, v67, v37
	v_cvt_pk_bf16_f32 v90, v16, v17
	v_mul_f32_e32 v16, v67, v38
	v_mul_f32_e32 v17, v67, v39
	v_cvt_pk_bf16_f32 v91, v16, v17
	v_mul_f32_e32 v16, v67, v40
	v_mul_f32_e32 v17, v67, v41
	v_cvt_pk_bf16_f32 v92, v16, v17
	v_mul_f32_e32 v16, v67, v42
	v_mul_f32_e32 v17, v67, v43
	v_cvt_pk_bf16_f32 v93, v16, v17
	v_mul_f32_e32 v16, v67, v44
	v_mul_f32_e32 v17, v67, v45
	v_cvt_pk_bf16_f32 v94, v16, v17
	v_mul_f32_e32 v16, v67, v46
	v_mul_f32_e32 v17, v67, v47
	v_cvt_pk_bf16_f32 v95, v16, v17
	v_mul_f32_e32 v16, v67, v48
	v_mul_f32_e32 v17, v67, v49
	v_cvt_pk_bf16_f32 v76, v16, v17
	v_mul_f32_e32 v16, v67, v50
	v_mul_f32_e32 v17, v67, v51
	v_cvt_pk_bf16_f32 v77, v16, v17
	v_mul_f32_e32 v16, v67, v52
	v_mul_f32_e32 v17, v67, v53
	v_cvt_pk_bf16_f32 v78, v16, v17
	v_mul_f32_e32 v16, v67, v54
	v_mul_f32_e32 v17, v67, v55
	v_cvt_pk_bf16_f32 v79, v16, v17
	v_mul_f32_e32 v16, v67, v56
	v_mul_f32_e32 v17, v67, v57
	v_cvt_pk_bf16_f32 v72, v16, v17
	v_mul_f32_e32 v16, v67, v58
	v_mul_f32_e32 v17, v67, v59
	v_cvt_pk_bf16_f32 v73, v16, v17
	v_mul_f32_e32 v16, v67, v60
	v_mul_f32_e32 v17, v67, v61
	v_mul_f32_e32 v0, v67, v0
	v_mul_f32_e32 v1, v67, v1
	v_cvt_pk_bf16_f32 v74, v16, v17
	v_mul_f32_e32 v16, v67, v62
	v_mul_f32_e32 v17, v67, v63
	v_cvt_pk_bf16_f32 v75, v16, v17
	v_cvt_pk_bf16_f32 v68, v0, v1
	v_mul_f32_e32 v0, v67, v2
	v_mul_f32_e32 v1, v67, v3
	v_cvt_pk_bf16_f32 v69, v0, v1
	v_mul_f32_e32 v0, v67, v4
	v_mul_f32_e32 v1, v67, v5
	v_cvt_pk_bf16_f32 v70, v0, v1
	v_mul_f32_e32 v0, v67, v6
	v_mul_f32_e32 v1, v67, v7
	s_lshl_b32 s16, s0, 8
	v_cvt_pk_bf16_f32 v71, v0, v1
	v_mul_f32_e32 v0, v67, v8
	v_mul_f32_e32 v1, v67, v9
	s_add_u32 s14, s14, s16
	v_cvt_pk_bf16_f32 v64, v0, v1
	v_mul_f32_e32 v0, v67, v10
	v_mul_f32_e32 v1, v67, v11
	s_addc_u32 s15, s15, 0
	v_cvt_pk_bf16_f32 v65, v0, v1
	v_mul_f32_e32 v0, v67, v12
	v_mul_f32_e32 v1, v67, v13
	s_lshl_b32 s0, s0, 15
	v_cvt_pk_bf16_f32 v66, v0, v1
	v_mul_f32_e32 v0, v67, v14
	v_mul_f32_e32 v1, v67, v15
	v_lshl_add_u64 v[62:63], v[152:153], 0, s[0:1]
	v_lshlrev_b32_e32 v194, 3, v172
	v_mov_b32_e32 v195, 0
	v_lshl_add_u64 v[62:63], v[62:63], 0, v[194:195]
	v_cvt_pk_bf16_f32 v67, v0, v1
	global_load_dwordx4 v[0:3], v[62:63], off
	global_load_dwordx4 v[16:19], v[62:63], off offset:32
	global_load_dwordx4 v[20:23], v[62:63], off offset:64
	global_load_dwordx4 v[24:27], v[62:63], off offset:96
	global_load_dwordx4 v[28:31], v[62:63], off offset:128
	v_add_co_u32_e32 v48, vcc, s36, v62
	s_waitcnt vmcnt(0)
	v_permlane32_swap_b32_e32 v0, v2
	v_permlane32_swap_b32_e32 v1, v3
	v_permlane32_swap_b32_e32 v16, v18
	v_permlane32_swap_b32_e32 v17, v19
	v_permlane32_swap_b32_e32 v20, v22
	v_permlane32_swap_b32_e32 v21, v23
	v_permlane32_swap_b32_e32 v24, v26
	v_permlane32_swap_b32_e32 v25, v27
	v_permlane32_swap_b32_e32 v28, v30
	v_permlane32_swap_b32_e32 v29, v31
	s_nop 1
	v_mfma_f32_32x32x16_bf16 v[0:15], v[0:3], v[80:83], 0
	v_addc_co_u32_e32 v49, vcc, 0, v63, vcc
	v_add_co_u32_e32 v138, vcc, s37, v62
	s_add_i32 s41, s41, s60
	s_nop 0
	v_addc_co_u32_e32 v139, vcc, 0, v63, vcc
	v_mfma_f32_32x32x16_bf16 v[0:15], v[16:19], v[84:87], v[0:15]
	global_load_dwordx4 v[16:19], v[62:63], off offset:160
	v_add_co_u32_e32 v146, vcc, s40, v62
	s_cmpk_gt_i32 s41, 0x7ff
	s_nop 0
	v_addc_co_u32_e32 v147, vcc, 0, v63, vcc
	v_mfma_f32_32x32x16_bf16 v[0:15], v[20:23], v[88:91], v[0:15]
	global_load_dwordx4 v[20:23], v[62:63], off offset:192
	v_mfma_f32_32x32x16_bf16 v[0:15], v[24:27], v[92:95], v[0:15]
	global_load_dwordx4 v[24:27], v[48:49], off
	global_load_dwordx4 v[32:35], v[62:63], off offset:224
	global_load_dwordx4 v[36:39], v[48:49], off offset:32
	global_load_dwordx4 v[40:43], v[48:49], off offset:64
	global_load_dwordx4 v[44:47], v[48:49], off offset:96
	v_lshl_add_u64 v[62:63], s[14:15], 0, v[154:155]
	v_lshl_add_u64 v[96:97], v[62:63], 0, v[150:151]
	v_lshlrev_b32_e32 v198, 3, v172
	v_mov_b32_e32 v199, 0
	v_lshl_add_u64 v[198:199], v[96:97], 0, v[198:199]
	v_mfma_f32_32x32x16_bf16 v[0:15], v[28:31], v[76:79], v[0:15]
	s_waitcnt vmcnt(0)
	v_permlane32_swap_b32_e32 v16, v18
	v_permlane32_swap_b32_e32 v17, v19
	v_permlane32_swap_b32_e32 v20, v22
	v_permlane32_swap_b32_e32 v21, v23
	v_permlane32_swap_b32_e32 v24, v26
	v_permlane32_swap_b32_e32 v25, v27
	v_permlane32_swap_b32_e32 v32, v34
	v_permlane32_swap_b32_e32 v33, v35
	v_permlane32_swap_b32_e32 v36, v38
	v_permlane32_swap_b32_e32 v37, v39
	v_permlane32_swap_b32_e32 v40, v42
	v_permlane32_swap_b32_e32 v41, v43
	v_permlane32_swap_b32_e32 v44, v46
	v_permlane32_swap_b32_e32 v45, v47
	s_nop 1
	v_mfma_f32_32x32x16_bf16 v[0:15], v[16:19], v[72:75], v[0:15]
	v_mfma_f32_32x32x16_bf16 v[0:15], v[20:23], v[68:71], v[0:15]
	v_mfma_f32_32x32x16_bf16 v[0:15], v[32:35], v[64:67], v[0:15]
	global_load_dwordx4 v[32:35], v[138:139], off
	global_load_dwordx4 v[50:53], v[138:139], off offset:32
	global_load_dwordx4 v[54:57], v[138:139], off offset:64
	global_load_dwordx4 v[58:61], v[138:139], off offset:96
	global_load_dwordx4 v[98:101], v[146:147], off
	global_load_dwordx4 v[102:105], v[146:147], off offset:32
	global_load_dwordx4 v[106:109], v[146:147], off offset:64
	global_load_dwordx2 v[158:159], v[96:97], off
	v_mfma_f32_32x32x16_bf16 v[16:31], v[24:27], v[80:83], 0
	global_load_dwordx4 v[110:113], v[146:147], off offset:96
	global_load_dwordx4 v[114:117], v[48:49], off offset:128
	global_load_dwordx4 v[118:121], v[48:49], off offset:160
	global_load_dwordx4 v[122:125], v[48:49], off offset:192
	global_load_dwordx4 v[126:129], v[48:49], off offset:224
	global_load_dwordx4 v[130:133], v[138:139], off offset:128
	global_load_dwordx4 v[134:137], v[138:139], off offset:160
	v_mfma_f32_32x32x16_bf16 v[16:31], v[36:39], v[84:87], v[16:31]
	v_mfma_f32_32x32x16_bf16 v[16:31], v[40:43], v[88:91], v[16:31]
	v_mfma_f32_32x32x16_bf16 v[16:31], v[44:47], v[92:95], v[16:31]
	s_waitcnt vmcnt(0)
	v_permlane32_swap_b32_e32 v32, v34
	v_permlane32_swap_b32_e32 v33, v35
	v_permlane32_swap_b32_e32 v50, v52
	v_permlane32_swap_b32_e32 v51, v53
	v_permlane32_swap_b32_e32 v54, v56
	v_permlane32_swap_b32_e32 v55, v57
	v_permlane32_swap_b32_e32 v58, v60
	v_permlane32_swap_b32_e32 v59, v61
	v_permlane32_swap_b32_e32 v98, v100
	v_permlane32_swap_b32_e32 v99, v101
	v_permlane32_swap_b32_e32 v102, v104
	v_permlane32_swap_b32_e32 v103, v105
	v_permlane32_swap_b32_e32 v106, v108
	v_permlane32_swap_b32_e32 v107, v109
	v_permlane32_swap_b32_e32 v110, v112
	v_permlane32_swap_b32_e32 v111, v113
	v_permlane32_swap_b32_e32 v114, v116
	v_permlane32_swap_b32_e32 v115, v117
	v_permlane32_swap_b32_e32 v118, v120
	v_permlane32_swap_b32_e32 v119, v121
	v_permlane32_swap_b32_e32 v122, v124
	v_permlane32_swap_b32_e32 v123, v125
	v_permlane32_swap_b32_e32 v126, v128
	v_permlane32_swap_b32_e32 v127, v129
	v_permlane32_swap_b32_e32 v130, v132
	v_permlane32_swap_b32_e32 v131, v133
	v_permlane32_swap_b32_e32 v134, v136
	v_permlane32_swap_b32_e32 v135, v137
	s_nop 1
	v_mfma_f32_32x32x16_bf16 v[32:47], v[32:35], v[80:83], 0
	v_mfma_f32_32x32x16_bf16 v[32:47], v[50:53], v[84:87], v[32:47]
	v_mfma_f32_32x32x16_bf16 v[32:47], v[54:57], v[88:91], v[32:47]
	v_mfma_f32_32x32x16_bf16 v[32:47], v[58:61], v[92:95], v[32:47]
	v_mfma_f32_32x32x16_bf16 v[48:63], v[98:101], v[80:83], 0
	global_load_dwordx4 v[80:83], v[138:139], off offset:192
	global_load_dwordx4 v[98:101], v[138:139], off offset:224
	s_nop 0
	global_load_dwordx4 v[138:141], v[146:147], off offset:128
	global_load_dwordx4 v[142:145], v[146:147], off offset:160
	v_mfma_f32_32x32x16_bf16 v[48:63], v[102:105], v[84:87], v[48:63]
	global_load_dwordx4 v[84:87], v[146:147], off offset:192
	global_load_dwordx4 v[102:105], v[146:147], off offset:224
	v_lshlrev_b32_e32 v146, 16, v158
	v_and_b32_e32 v147, 0xffff0000, v158
	v_lshlrev_b32_e32 v158, 16, v159
	v_mul_f32_e32 v0, v0, v146
	v_mul_f32_e32 v1, v1, v147
	v_cvt_pk_bf16_f32 v0, v0, v1
	v_mfma_f32_32x32x16_bf16 v[48:63], v[106:109], v[88:91], v[48:63]
	v_and_b32_e32 v88, 0xffff0000, v159
	v_mul_f32_e32 v1, v2, v158
	v_mul_f32_e32 v2, v3, v88
	v_cvt_pk_bf16_f32 v1, v1, v2
	s_nop 0
	v_mov_b32_e32 v200, v0
	v_mov_b32_e32 v201, v1
	v_mfma_f32_32x32x16_bf16 v[16:31], v[114:117], v[76:79], v[16:31]
	s_waitcnt vmcnt(0)
	v_permlane32_swap_b32_e32 v80, v82
	v_permlane32_swap_b32_e32 v81, v83
	v_permlane32_swap_b32_e32 v98, v100
	v_permlane32_swap_b32_e32 v99, v101
	v_permlane32_swap_b32_e32 v138, v140
	v_permlane32_swap_b32_e32 v139, v141
	v_permlane32_swap_b32_e32 v142, v144
	v_permlane32_swap_b32_e32 v143, v145
	v_permlane32_swap_b32_e32 v84, v86
	v_permlane32_swap_b32_e32 v85, v87
	v_permlane32_swap_b32_e32 v102, v104
	v_permlane32_swap_b32_e32 v103, v105
	s_nop 1
	v_lshlrev_b32_e32 v0, 16, v208
	v_and_b32_e32 v1, 0xffff0000, v208
	v_lshlrev_b32_e32 v2, 16, v209
	v_and_b32_e32 v3, 0xffff0000, v209
	v_mul_f32_e32 v0, v4, v0
	v_mul_f32_e32 v1, v5, v1
	v_mul_f32_e32 v2, v6, v2
	v_mul_f32_e32 v3, v7, v3
	v_cvt_pk_bf16_f32 v0, v0, v1
	v_cvt_pk_bf16_f32 v1, v2, v3
	v_mfma_f32_32x32x16_bf16 v[16:31], v[118:121], v[72:75], v[16:31]
	v_mov_b32_e32 v202, v0
	v_mov_b32_e32 v203, v1
	s_nop 1
	v_permlane32_swap_b32_e32 v200, v202
	v_permlane32_swap_b32_e32 v201, v203
	global_store_dwordx4 v[198:199], v[200:203], off
	v_lshlrev_b32_e32 v0, 16, v210
	v_and_b32_e32 v1, 0xffff0000, v210
	v_lshlrev_b32_e32 v2, 16, v211
	v_and_b32_e32 v3, 0xffff0000, v211
	v_mul_f32_e32 v0, v8, v0
	v_mul_f32_e32 v1, v9, v1
	v_mul_f32_e32 v2, v10, v2
	v_mul_f32_e32 v3, v11, v3
	v_cvt_pk_bf16_f32 v0, v0, v1
	v_cvt_pk_bf16_f32 v1, v2, v3
	v_mfma_f32_32x32x16_bf16 v[16:31], v[122:125], v[68:71], v[16:31]
	v_mov_b32_e32 v200, v0
	v_mov_b32_e32 v201, v1
	v_lshlrev_b32_e32 v0, 16, v212
	v_and_b32_e32 v1, 0xffff0000, v212
	v_lshlrev_b32_e32 v2, 16, v213
	v_and_b32_e32 v3, 0xffff0000, v213
	v_mul_f32_e32 v0, v12, v0
	v_mul_f32_e32 v1, v13, v1
	v_mul_f32_e32 v2, v14, v2
	v_mul_f32_e32 v3, v15, v3
	v_cvt_pk_bf16_f32 v0, v0, v1
	v_cvt_pk_bf16_f32 v1, v2, v3
	v_mfma_f32_32x32x16_bf16 v[16:31], v[126:129], v[64:67], v[16:31]
	v_mov_b32_e32 v202, v0
	v_mov_b32_e32 v203, v1
	s_nop 1
	v_permlane32_swap_b32_e32 v200, v202
	v_permlane32_swap_b32_e32 v201, v203
	global_store_dwordx4 v[198:199], v[200:203], off offset:32
	v_lshlrev_b32_e32 v0, 16, v214
	v_and_b32_e32 v1, 0xffff0000, v214
	v_lshlrev_b32_e32 v2, 16, v215
	v_and_b32_e32 v3, 0xffff0000, v215
	s_nop 5
	v_mul_f32_e32 v0, v16, v0
	v_mul_f32_e32 v1, v17, v1
	v_mul_f32_e32 v2, v18, v2
	v_mul_f32_e32 v3, v19, v3
	v_cvt_pk_bf16_f32 v0, v0, v1
	v_cvt_pk_bf16_f32 v1, v2, v3
	v_mfma_f32_32x32x16_bf16 v[32:47], v[130:133], v[76:79], v[32:47]
	v_mov_b32_e32 v200, v0
	v_mov_b32_e32 v201, v1
	v_lshlrev_b32_e32 v0, 16, v216
	v_and_b32_e32 v1, 0xffff0000, v216
	v_lshlrev_b32_e32 v2, 16, v217
	v_and_b32_e32 v3, 0xffff0000, v217
	v_mul_f32_e32 v0, v20, v0
	v_mul_f32_e32 v1, v21, v1
	v_mul_f32_e32 v2, v22, v2
	v_mul_f32_e32 v3, v23, v3
	v_cvt_pk_bf16_f32 v0, v0, v1
	v_cvt_pk_bf16_f32 v1, v2, v3
	v_mfma_f32_32x32x16_bf16 v[32:47], v[134:137], v[72:75], v[32:47]
	v_mov_b32_e32 v202, v0
	v_mov_b32_e32 v203, v1
	s_nop 1
	v_permlane32_swap_b32_e32 v200, v202
	v_permlane32_swap_b32_e32 v201, v203
	global_store_dwordx4 v[198:199], v[200:203], off offset:64
	v_lshlrev_b32_e32 v0, 16, v218
	v_and_b32_e32 v1, 0xffff0000, v218
	v_lshlrev_b32_e32 v2, 16, v219
	v_and_b32_e32 v3, 0xffff0000, v219
	v_mul_f32_e32 v0, v24, v0
	v_mul_f32_e32 v1, v25, v1
	v_mul_f32_e32 v2, v26, v2
	v_mul_f32_e32 v3, v27, v3
	v_cvt_pk_bf16_f32 v0, v0, v1
	v_cvt_pk_bf16_f32 v1, v2, v3
	v_mfma_f32_32x32x16_bf16 v[32:47], v[80:83], v[68:71], v[32:47]
	v_mov_b32_e32 v200, v0
	v_mov_b32_e32 v201, v1
	v_lshlrev_b32_e32 v0, 16, v220
	v_and_b32_e32 v1, 0xffff0000, v220
	v_lshlrev_b32_e32 v2, 16, v221
	v_and_b32_e32 v3, 0xffff0000, v221
	v_mul_f32_e32 v0, v28, v0
	v_mul_f32_e32 v1, v29, v1
	v_mul_f32_e32 v2, v30, v2
	v_mul_f32_e32 v3, v31, v3
	v_cvt_pk_bf16_f32 v0, v0, v1
	v_cvt_pk_bf16_f32 v1, v2, v3
	v_mfma_f32_32x32x16_bf16 v[32:47], v[98:101], v[64:67], v[32:47]
	v_mov_b32_e32 v202, v0
	v_mov_b32_e32 v203, v1
	s_nop 1
	v_permlane32_swap_b32_e32 v200, v202
	v_permlane32_swap_b32_e32 v201, v203
	global_store_dwordx4 v[198:199], v[200:203], off offset:96
	v_lshlrev_b32_e32 v0, 16, v222
	v_and_b32_e32 v1, 0xffff0000, v222
	v_lshlrev_b32_e32 v2, 16, v223
	v_and_b32_e32 v3, 0xffff0000, v223
	s_nop 5
	v_mul_f32_e32 v0, v32, v0
	v_mul_f32_e32 v1, v33, v1
	v_mul_f32_e32 v2, v34, v2
	v_mul_f32_e32 v3, v35, v3
	v_cvt_pk_bf16_f32 v0, v0, v1
	v_cvt_pk_bf16_f32 v1, v2, v3
	v_mfma_f32_32x32x16_bf16 v[48:63], v[110:113], v[92:95], v[48:63]
	v_mov_b32_e32 v200, v0
	v_mov_b32_e32 v201, v1
	v_lshlrev_b32_e32 v0, 16, v224
	v_and_b32_e32 v1, 0xffff0000, v224
	v_lshlrev_b32_e32 v2, 16, v225
	v_and_b32_e32 v3, 0xffff0000, v225
	v_mul_f32_e32 v0, v36, v0
	v_mul_f32_e32 v1, v37, v1
	v_mul_f32_e32 v2, v38, v2
	v_mul_f32_e32 v3, v39, v3
	v_cvt_pk_bf16_f32 v0, v0, v1
	v_cvt_pk_bf16_f32 v1, v2, v3
	v_mfma_f32_32x32x16_bf16 v[48:63], v[138:141], v[76:79], v[48:63]
	v_mov_b32_e32 v202, v0
	v_mov_b32_e32 v203, v1
	s_nop 1
	v_permlane32_swap_b32_e32 v200, v202
	v_permlane32_swap_b32_e32 v201, v203
	global_store_dwordx4 v[198:199], v[200:203], off offset:128
	v_lshlrev_b32_e32 v0, 16, v226
	v_and_b32_e32 v1, 0xffff0000, v226
	v_lshlrev_b32_e32 v2, 16, v227
	v_and_b32_e32 v3, 0xffff0000, v227
	v_mul_f32_e32 v0, v40, v0
	v_mul_f32_e32 v1, v41, v1
	v_mul_f32_e32 v2, v42, v2
	v_mul_f32_e32 v3, v43, v3
	v_cvt_pk_bf16_f32 v0, v0, v1
	v_cvt_pk_bf16_f32 v1, v2, v3
	v_mfma_f32_32x32x16_bf16 v[48:63], v[142:145], v[72:75], v[48:63]
	v_mov_b32_e32 v200, v0
	v_mov_b32_e32 v201, v1
	v_lshlrev_b32_e32 v0, 16, v228
	v_and_b32_e32 v1, 0xffff0000, v228
	v_lshlrev_b32_e32 v2, 16, v229
	v_and_b32_e32 v3, 0xffff0000, v229
	v_mul_f32_e32 v0, v44, v0
	v_mul_f32_e32 v1, v45, v1
	v_mul_f32_e32 v2, v46, v2
	v_mul_f32_e32 v3, v47, v3
	v_cvt_pk_bf16_f32 v0, v0, v1
	v_cvt_pk_bf16_f32 v1, v2, v3
	v_mfma_f32_32x32x16_bf16 v[48:63], v[84:87], v[68:71], v[48:63]
	v_mov_b32_e32 v202, v0
	v_mov_b32_e32 v203, v1
	s_nop 1
	v_permlane32_swap_b32_e32 v200, v202
	v_permlane32_swap_b32_e32 v201, v203
	global_store_dwordx4 v[198:199], v[200:203], off offset:160
	v_lshlrev_b32_e32 v0, 16, v230
	v_mfma_f32_32x32x16_bf16 v[48:63], v[102:105], v[64:67], v[48:63]
	v_and_b32_e32 v1, 0xffff0000, v230
	v_lshlrev_b32_e32 v2, 16, v231
	v_and_b32_e32 v3, 0xffff0000, v231
	s_nop 8
	v_mul_f32_e32 v0, v48, v0
	v_mul_f32_e32 v1, v49, v1
	v_mul_f32_e32 v2, v50, v2
	v_mul_f32_e32 v3, v51, v3
	v_cvt_pk_bf16_f32 v0, v0, v1
	v_cvt_pk_bf16_f32 v1, v2, v3
	s_nop 0
	v_mov_b32_e32 v200, v0
	v_mov_b32_e32 v201, v1
	v_lshlrev_b32_e32 v0, 16, v232
	v_and_b32_e32 v1, 0xffff0000, v232
	v_lshlrev_b32_e32 v2, 16, v233
	v_and_b32_e32 v3, 0xffff0000, v233
	v_mul_f32_e32 v0, v52, v0
	v_mul_f32_e32 v1, v53, v1
	v_mul_f32_e32 v2, v54, v2
	v_mul_f32_e32 v3, v55, v3
	v_cvt_pk_bf16_f32 v0, v0, v1
	v_cvt_pk_bf16_f32 v1, v2, v3
	s_nop 0
	v_mov_b32_e32 v202, v0
	v_mov_b32_e32 v203, v1
	s_nop 1
	v_permlane32_swap_b32_e32 v200, v202
	v_permlane32_swap_b32_e32 v201, v203
	global_store_dwordx4 v[198:199], v[200:203], off offset:192
	v_lshlrev_b32_e32 v0, 16, v234
	v_and_b32_e32 v1, 0xffff0000, v234
	v_lshlrev_b32_e32 v2, 16, v235
	v_and_b32_e32 v3, 0xffff0000, v235
	v_mul_f32_e32 v0, v56, v0
	v_mul_f32_e32 v1, v57, v1
	v_mul_f32_e32 v2, v58, v2
	v_mul_f32_e32 v3, v59, v3
	v_cvt_pk_bf16_f32 v0, v0, v1
	v_cvt_pk_bf16_f32 v1, v2, v3
	s_nop 0
	v_mov_b32_e32 v200, v0
	v_mov_b32_e32 v201, v1
	v_lshlrev_b32_e32 v0, 16, v236
	v_and_b32_e32 v1, 0xffff0000, v236
	v_lshlrev_b32_e32 v2, 16, v237
	v_and_b32_e32 v3, 0xffff0000, v237
	v_mul_f32_e32 v0, v60, v0
	v_mul_f32_e32 v1, v61, v1
	v_mul_f32_e32 v2, v62, v2
	v_mul_f32_e32 v3, v63, v3
	v_cvt_pk_bf16_f32 v0, v0, v1
	v_cvt_pk_bf16_f32 v1, v2, v3
	v_mov_b32_e32 v202, v0
	v_mov_b32_e32 v203, v1
	s_nop 1
	v_permlane32_swap_b32_e32 v200, v202
	v_permlane32_swap_b32_e32 v201, v203
	global_store_dwordx4 v[198:199], v[200:203], off offset:224
	s_waitcnt lgkmcnt(0)
	s_barrier
	s_cbranch_scc1 .LBB0_525

.LBB0_519:
	s_lshl_b64 s[98:99], s[14:15], 12
	s_add_u32 s98, s23, s98
	s_addc_u32 s99, s24, s99
	s_lshl_b32 s100, s0, 8
	s_add_u32 s98, s98, s100
	s_addc_u32 s99, s99, 0
	v_lshl_add_u64 v[208:209], s[98:99], 0, v[154:155]
	v_lshl_add_u64 v[208:209], v[208:209], 0, v[150:151]
	v_lshlrev_b32_e32 v196, 3, v172
	v_mov_b32_e32 v197, 0
	v_lshl_add_u64 v[196:197], v[208:209], 0, v[196:197]
	global_load_dwordx4 v[210:213], v[196:197], off offset:32
	global_load_dwordx4 v[214:217], v[196:197], off offset:64
	global_load_dwordx4 v[218:221], v[196:197], off offset:96
	global_load_dwordx4 v[222:225], v[196:197], off offset:128
	global_load_dwordx4 v[226:229], v[196:197], off offset:160
	global_load_dwordx4 v[230:233], v[196:197], off offset:192
	global_load_dwordx4 v[234:237], v[196:197], off offset:224
	global_load_dwordx2 v[208:209], v[208:209], off offset:16
	s_nop 4
	v_max_f32_e32 v96, v81, v81
	v_max_f32_e32 v97, v80, v80
	v_max_f32_e32 v96, v97, v96
	v_max3_f32 v96, v96, v82, v83
	v_max3_f32 v96, v96, v84, v85
	v_max3_f32 v96, v96, v86, v87
	v_max3_f32 v96, v96, v88, v89
	v_max3_f32 v96, v96, v90, v91
	v_max3_f32 v96, v96, v92, v93
	v_max3_f32 v96, v96, v94, v95
	v_max3_f32 v96, v96, v64, v65
	v_max3_f32 v96, v96, v66, v67
	v_max3_f32 v96, v96, v68, v69
	v_max3_f32 v96, v96, v70, v71
	v_max3_f32 v96, v96, v72, v73
	v_max3_f32 v96, v96, v74, v75
	v_max3_f32 v96, v96, v76, v77
	v_max3_f32 v96, v96, v78, v79
	v_mov_b32_e32 v97, v96
	s_nop 1
	v_permlane32_swap_b32_e32 v96, v97
	v_max_f32_e32 v97, v97, v97
	v_max_f32_e32 v96, v96, v96
	v_max_f32_e32 v97, v96, v97
	v_cmp_ge_f32_e32 vcc, s39, v97
	s_cmp_eq_u64 vcc, exec
	v_mov_b32_e32 v96, 1.0
	s_cbranch_scc0 .LBB0_524
	v_cmp_gt_f32_e32 vcc, 1.0, v96
	s_cbranch_vccz .LBB0_522

.LBB0_527:
	s_or_b64 exec, exec, s[8:9]
	s_nop 0
	v_rcp_f32_e32 v67, v96
	s_lshl_b64 s[6:7], s[6:7], 12
	s_add_u32 s6, s23, s6
	s_addc_u32 s7, s24, s7
	v_mul_f32_e32 v0, v67, v0
	v_mul_f32_e32 v1, v67, v1
	v_cvt_pk_bf16_f32 v80, v0, v1
	v_mul_f32_e32 v0, v67, v2
	v_mul_f32_e32 v1, v67, v3
	v_cvt_pk_bf16_f32 v81, v0, v1
	v_mul_f32_e32 v0, v67, v4
	v_mul_f32_e32 v1, v67, v5
	v_cvt_pk_bf16_f32 v82, v0, v1
	v_mul_f32_e32 v0, v67, v6
	v_mul_f32_e32 v1, v67, v7
	v_cvt_pk_bf16_f32 v83, v0, v1
	v_mul_f32_e32 v0, v67, v8
	v_mul_f32_e32 v1, v67, v9
	v_cvt_pk_bf16_f32 v84, v0, v1
	v_mul_f32_e32 v0, v67, v10
	v_mul_f32_e32 v1, v67, v11
	v_cvt_pk_bf16_f32 v85, v0, v1
	v_mul_f32_e32 v0, v67, v12
	v_mul_f32_e32 v1, v67, v13
	v_cvt_pk_bf16_f32 v86, v0, v1
	v_mul_f32_e32 v0, v67, v14
	v_mul_f32_e32 v1, v67, v15
	v_cvt_pk_bf16_f32 v87, v0, v1
	v_mul_f32_e32 v0, v67, v16
	v_mul_f32_e32 v1, v67, v17
	v_cvt_pk_bf16_f32 v88, v0, v1
	v_mul_f32_e32 v0, v67, v18
	v_mul_f32_e32 v1, v67, v19
	v_cvt_pk_bf16_f32 v89, v0, v1
	v_mul_f32_e32 v0, v67, v20
	v_mul_f32_e32 v1, v67, v21
	v_cvt_pk_bf16_f32 v90, v0, v1
	v_mul_f32_e32 v0, v67, v22
	v_mul_f32_e32 v1, v67, v23
	v_cvt_pk_bf16_f32 v91, v0, v1
	v_mul_f32_e32 v0, v67, v24
	v_mul_f32_e32 v1, v67, v25
	v_cvt_pk_bf16_f32 v92, v0, v1
	v_mul_f32_e32 v0, v67, v26
	v_mul_f32_e32 v1, v67, v27
	v_cvt_pk_bf16_f32 v93, v0, v1
	v_mul_f32_e32 v0, v67, v28
	v_mul_f32_e32 v1, v67, v29
	v_cvt_pk_bf16_f32 v94, v0, v1
	v_mul_f32_e32 v0, v67, v30
	v_mul_f32_e32 v1, v67, v31
	v_cvt_pk_bf16_f32 v95, v0, v1
	v_mul_f32_e32 v0, v67, v32
	v_mul_f32_e32 v1, v67, v33
	v_cvt_pk_bf16_f32 v76, v0, v1
	v_mul_f32_e32 v0, v67, v34
	v_mul_f32_e32 v1, v67, v35
	v_cvt_pk_bf16_f32 v77, v0, v1
	v_mul_f32_e32 v0, v67, v36
	v_mul_f32_e32 v1, v67, v37
	v_cvt_pk_bf16_f32 v78, v0, v1
	v_mul_f32_e32 v0, v67, v38
	v_mul_f32_e32 v1, v67, v39
	v_cvt_pk_bf16_f32 v79, v0, v1
	v_mul_f32_e32 v0, v67, v40
	v_mul_f32_e32 v1, v67, v41
	v_cvt_pk_bf16_f32 v72, v0, v1
	v_mul_f32_e32 v0, v67, v42
	v_mul_f32_e32 v1, v67, v43
	v_cvt_pk_bf16_f32 v73, v0, v1
	v_mul_f32_e32 v0, v67, v44
	v_mul_f32_e32 v1, v67, v45
	v_cvt_pk_bf16_f32 v74, v0, v1
	v_mul_f32_e32 v0, v67, v46
	v_mul_f32_e32 v1, v67, v47
	v_cvt_pk_bf16_f32 v75, v0, v1
	v_mul_f32_e32 v0, v67, v48
	v_mul_f32_e32 v1, v67, v49
	v_cvt_pk_bf16_f32 v68, v0, v1
	v_mul_f32_e32 v0, v67, v50
	v_mul_f32_e32 v1, v67, v51
	v_cvt_pk_bf16_f32 v69, v0, v1
	v_mul_f32_e32 v0, v67, v52
	v_mul_f32_e32 v1, v67, v53
	v_cvt_pk_bf16_f32 v70, v0, v1
	v_mul_f32_e32 v0, v67, v54
	v_mul_f32_e32 v1, v67, v55
	s_lshl_b32 s8, s0, 8
	v_cvt_pk_bf16_f32 v71, v0, v1
	v_mul_f32_e32 v0, v67, v56
	v_mul_f32_e32 v1, v67, v57
	s_add_u32 s6, s6, s8
	v_cvt_pk_bf16_f32 v64, v0, v1
	v_mul_f32_e32 v0, v67, v58
	v_mul_f32_e32 v1, v67, v59
	s_addc_u32 s7, s7, 0
	v_lshl_add_u64 v[150:151], s[6:7], 0, v[200:201]
	v_lshl_add_u64 v[150:151], v[150:151], 0, v[196:197]
	v_bfe_u32 v190, v192, 5, 1
	v_lshlrev_b32_e32 v190, 3, v190
	v_mov_b32_e32 v191, 0
	v_lshl_add_u64 v[190:191], v[150:151], 0, v[190:191]
	global_load_dwordx4 v[152:155], v[190:191], off offset:32
	global_load_dwordx4 v[156:159], v[190:191], off offset:64
	global_load_dwordx4 v[160:163], v[190:191], off offset:96
	global_load_dwordx4 v[164:167], v[190:191], off offset:128
	global_load_dwordx4 v[168:171], v[190:191], off offset:160
	global_load_dwordx4 v[172:175], v[190:191], off offset:192
	global_load_dwordx4 v[176:179], v[190:191], off offset:224
	global_load_dwordx2 v[150:151], v[150:151], off offset:16
	v_cvt_pk_bf16_f32 v65, v0, v1
	v_mul_f32_e32 v0, v67, v60
	v_mul_f32_e32 v1, v67, v61
	s_lshl_b32 s0, s0, 15
	v_cvt_pk_bf16_f32 v66, v0, v1
	v_mul_f32_e32 v0, v67, v62
	v_mul_f32_e32 v1, v67, v63
	v_lshl_add_u64 v[62:63], v[198:199], 0, s[0:1]
	v_bfe_u32 v188, v192, 5, 1
	v_lshlrev_b32_e32 v188, 3, v188
	v_mov_b32_e32 v189, 0
	v_lshl_add_u64 v[62:63], v[62:63], 0, v[188:189]
	v_cvt_pk_bf16_f32 v67, v0, v1
	global_load_dwordx4 v[0:3], v[62:63], off
	global_load_dwordx4 v[16:19], v[62:63], off offset:32
	global_load_dwordx4 v[20:23], v[62:63], off offset:64
	global_load_dwordx4 v[24:27], v[62:63], off offset:96
	global_load_dwordx4 v[28:31], v[62:63], off offset:128
	v_add_co_u32_e32 v48, vcc, s27, v62
	s_add_i32 s20, s20, s60
	s_waitcnt vmcnt(0)
	v_permlane32_swap_b32_e32 v152, v154
	v_permlane32_swap_b32_e32 v153, v155
	v_permlane32_swap_b32_e32 v156, v158
	v_permlane32_swap_b32_e32 v157, v159
	v_permlane32_swap_b32_e32 v160, v162
	v_permlane32_swap_b32_e32 v161, v163
	v_permlane32_swap_b32_e32 v164, v166
	v_permlane32_swap_b32_e32 v165, v167
	v_permlane32_swap_b32_e32 v168, v170
	v_permlane32_swap_b32_e32 v169, v171
	v_permlane32_swap_b32_e32 v172, v174
	v_permlane32_swap_b32_e32 v173, v175
	v_permlane32_swap_b32_e32 v176, v178
	v_permlane32_swap_b32_e32 v177, v179
	v_permlane32_swap_b32_e32 v0, v2
	v_permlane32_swap_b32_e32 v1, v3
	v_permlane32_swap_b32_e32 v16, v18
	v_permlane32_swap_b32_e32 v17, v19
	v_permlane32_swap_b32_e32 v20, v22
	v_permlane32_swap_b32_e32 v21, v23
	v_permlane32_swap_b32_e32 v24, v26
	v_permlane32_swap_b32_e32 v25, v27
	v_permlane32_swap_b32_e32 v28, v30
	v_permlane32_swap_b32_e32 v29, v31
	s_nop 1
	v_mfma_f32_32x32x16_bf16 v[0:15], v[0:3], v[80:83], 0
	v_addc_co_u32_e32 v49, vcc, 0, v63, vcc
	v_add_co_u32_e32 v138, vcc, s17, v62
	s_cmpk_lt_i32 s20, 0x200
	s_nop 0
	v_addc_co_u32_e32 v139, vcc, 0, v63, vcc
	v_mfma_f32_32x32x16_bf16 v[0:15], v[16:19], v[84:87], v[0:15]
	global_load_dwordx4 v[16:19], v[62:63], off offset:160
	v_add_co_u32_e32 v146, vcc, s28, v62
	s_nop 1
	v_addc_co_u32_e32 v147, vcc, 0, v63, vcc
	v_mfma_f32_32x32x16_bf16 v[0:15], v[20:23], v[88:91], v[0:15]
	global_load_dwordx4 v[20:23], v[48:49], off
	global_load_dwordx4 v[32:35], v[62:63], off offset:192
	global_load_dwordx4 v[36:39], v[62:63], off offset:224
	global_load_dwordx4 v[40:43], v[48:49], off offset:32
	global_load_dwordx4 v[44:47], v[48:49], off offset:64
	v_lshl_add_u64 v[62:63], s[6:7], 0, v[200:201]
	v_lshl_add_u64 v[96:97], v[62:63], 0, v[196:197]
	v_bfe_u32 v180, v192, 5, 1
	v_lshlrev_b32_e32 v180, 3, v180
	v_mov_b32_e32 v181, 0
	v_lshl_add_u64 v[180:181], v[96:97], 0, v[180:181]
	v_mfma_f32_32x32x16_bf16 v[0:15], v[24:27], v[92:95], v[0:15]
	v_mfma_f32_32x32x16_bf16 v[0:15], v[28:31], v[76:79], v[0:15]
	s_waitcnt vmcnt(0)
	v_permlane32_swap_b32_e32 v16, v18
	v_permlane32_swap_b32_e32 v17, v19
	v_permlane32_swap_b32_e32 v20, v22
	v_permlane32_swap_b32_e32 v21, v23
	v_permlane32_swap_b32_e32 v32, v34
	v_permlane32_swap_b32_e32 v33, v35
	v_permlane32_swap_b32_e32 v36, v38
	v_permlane32_swap_b32_e32 v37, v39
	v_permlane32_swap_b32_e32 v40, v42
	v_permlane32_swap_b32_e32 v41, v43
	v_permlane32_swap_b32_e32 v44, v46
	v_permlane32_swap_b32_e32 v45, v47
	s_nop 1
	v_mfma_f32_32x32x16_bf16 v[0:15], v[16:19], v[72:75], v[0:15]
	v_mfma_f32_32x32x16_bf16 v[0:15], v[32:35], v[68:71], v[0:15]
	global_load_dwordx4 v[32:35], v[48:49], off offset:96
	v_mfma_f32_32x32x16_bf16 v[0:15], v[36:39], v[64:67], v[0:15]
	global_load_dwordx4 v[36:39], v[138:139], off
	global_load_dwordx4 v[50:53], v[138:139], off offset:32
	global_load_dwordx4 v[54:57], v[138:139], off offset:64
	global_load_dwordx4 v[58:61], v[138:139], off offset:96
	global_load_dwordx4 v[98:101], v[146:147], off
	global_load_dwordx4 v[102:105], v[146:147], off offset:32
	global_load_dwordx4 v[106:109], v[146:147], off offset:64
	global_load_dwordx2 v[148:149], v[96:97], off
	v_mfma_f32_32x32x16_bf16 v[16:31], v[20:23], v[80:83], 0
	global_load_dwordx4 v[110:113], v[146:147], off offset:96
	global_load_dwordx4 v[114:117], v[48:49], off offset:128
	global_load_dwordx4 v[118:121], v[48:49], off offset:160
	global_load_dwordx4 v[122:125], v[48:49], off offset:192
	global_load_dwordx4 v[126:129], v[48:49], off offset:224
	global_load_dwordx4 v[130:133], v[138:139], off offset:128
	global_load_dwordx4 v[134:137], v[138:139], off offset:160
	v_mfma_f32_32x32x16_bf16 v[16:31], v[40:43], v[84:87], v[16:31]
	v_mfma_f32_32x32x16_bf16 v[16:31], v[44:47], v[88:91], v[16:31]
	s_waitcnt vmcnt(0)
	v_permlane32_swap_b32_e32 v32, v34
	v_permlane32_swap_b32_e32 v33, v35
	v_permlane32_swap_b32_e32 v36, v38
	v_permlane32_swap_b32_e32 v37, v39
	v_permlane32_swap_b32_e32 v50, v52
	v_permlane32_swap_b32_e32 v51, v53
	v_permlane32_swap_b32_e32 v54, v56
	v_permlane32_swap_b32_e32 v55, v57
	v_permlane32_swap_b32_e32 v58, v60
	v_permlane32_swap_b32_e32 v59, v61
	v_permlane32_swap_b32_e32 v98, v100
	v_permlane32_swap_b32_e32 v99, v101
	v_permlane32_swap_b32_e32 v102, v104
	v_permlane32_swap_b32_e32 v103, v105
	v_permlane32_swap_b32_e32 v106, v108
	v_permlane32_swap_b32_e32 v107, v109
	v_permlane32_swap_b32_e32 v110, v112
	v_permlane32_swap_b32_e32 v111, v113
	v_permlane32_swap_b32_e32 v114, v116
	v_permlane32_swap_b32_e32 v115, v117
	v_permlane32_swap_b32_e32 v118, v120
	v_permlane32_swap_b32_e32 v119, v121
	v_permlane32_swap_b32_e32 v122, v124
	v_permlane32_swap_b32_e32 v123, v125
	v_permlane32_swap_b32_e32 v126, v128
	v_permlane32_swap_b32_e32 v127, v129
	v_permlane32_swap_b32_e32 v130, v132
	v_permlane32_swap_b32_e32 v131, v133
	v_permlane32_swap_b32_e32 v134, v136
	v_permlane32_swap_b32_e32 v135, v137
	s_nop 1
	v_mfma_f32_32x32x16_bf16 v[16:31], v[32:35], v[92:95], v[16:31]
	v_mfma_f32_32x32x16_bf16 v[32:47], v[36:39], v[80:83], 0
	v_mfma_f32_32x32x16_bf16 v[32:47], v[50:53], v[84:87], v[32:47]
	v_mfma_f32_32x32x16_bf16 v[32:47], v[54:57], v[88:91], v[32:47]
	v_mfma_f32_32x32x16_bf16 v[32:47], v[58:61], v[92:95], v[32:47]
	v_mfma_f32_32x32x16_bf16 v[48:63], v[98:101], v[80:83], 0
	global_load_dwordx4 v[80:83], v[138:139], off offset:192
	global_load_dwordx4 v[98:101], v[138:139], off offset:224
	s_nop 0
	global_load_dwordx4 v[138:141], v[146:147], off offset:128
	global_load_dwordx4 v[142:145], v[146:147], off offset:160
	v_mfma_f32_32x32x16_bf16 v[48:63], v[102:105], v[84:87], v[48:63]
	global_load_dwordx4 v[84:87], v[146:147], off offset:192
	global_load_dwordx4 v[102:105], v[146:147], off offset:224
	v_lshlrev_b32_e32 v146, 16, v148
	v_and_b32_e32 v147, 0xffff0000, v148
	v_lshlrev_b32_e32 v148, 16, v149
	v_mul_f32_e32 v0, v0, v146
	v_mul_f32_e32 v1, v1, v147
	v_cvt_pk_bf16_f32 v0, v0, v1
	v_mfma_f32_32x32x16_bf16 v[48:63], v[106:109], v[88:91], v[48:63]
	v_and_b32_e32 v88, 0xffff0000, v149
	v_mul_f32_e32 v1, v2, v148
	v_mul_f32_e32 v2, v3, v88
	v_cvt_pk_bf16_f32 v1, v1, v2
	s_nop 0
	v_mov_b32_e32 v184, v0
	v_mov_b32_e32 v185, v1
	v_mfma_f32_32x32x16_bf16 v[16:31], v[114:117], v[76:79], v[16:31]
	s_waitcnt vmcnt(0)
	v_permlane32_swap_b32_e32 v80, v82
	v_permlane32_swap_b32_e32 v81, v83
	v_permlane32_swap_b32_e32 v98, v100
	v_permlane32_swap_b32_e32 v99, v101
	v_permlane32_swap_b32_e32 v138, v140
	v_permlane32_swap_b32_e32 v139, v141
	v_permlane32_swap_b32_e32 v142, v144
	v_permlane32_swap_b32_e32 v143, v145
	v_permlane32_swap_b32_e32 v84, v86
	v_permlane32_swap_b32_e32 v85, v87
	v_permlane32_swap_b32_e32 v102, v104
	v_permlane32_swap_b32_e32 v103, v105
	s_nop 1
	v_lshlrev_b32_e32 v0, 16, v150
	v_and_b32_e32 v1, 0xffff0000, v150
	v_lshlrev_b32_e32 v2, 16, v151
	v_and_b32_e32 v3, 0xffff0000, v151
	v_mul_f32_e32 v0, v4, v0
	v_mul_f32_e32 v1, v5, v1
	v_mul_f32_e32 v2, v6, v2
	v_mul_f32_e32 v3, v7, v3
	v_cvt_pk_bf16_f32 v0, v0, v1
	v_cvt_pk_bf16_f32 v1, v2, v3
	v_mfma_f32_32x32x16_bf16 v[16:31], v[118:121], v[72:75], v[16:31]
	v_mov_b32_e32 v186, v0
	v_mov_b32_e32 v187, v1
	s_nop 1
	v_permlane32_swap_b32_e32 v184, v186
	v_permlane32_swap_b32_e32 v185, v187
	global_store_dwordx4 v[180:181], v[184:187], off
	v_lshlrev_b32_e32 v0, 16, v152
	v_and_b32_e32 v1, 0xffff0000, v152
	v_lshlrev_b32_e32 v2, 16, v153
	v_and_b32_e32 v3, 0xffff0000, v153
	v_mul_f32_e32 v0, v8, v0
	v_mul_f32_e32 v1, v9, v1
	v_mul_f32_e32 v2, v10, v2
	v_mul_f32_e32 v3, v11, v3
	v_cvt_pk_bf16_f32 v0, v0, v1
	v_cvt_pk_bf16_f32 v1, v2, v3
	v_mfma_f32_32x32x16_bf16 v[16:31], v[122:125], v[68:71], v[16:31]
	v_mov_b32_e32 v184, v0
	v_mov_b32_e32 v185, v1
	v_lshlrev_b32_e32 v0, 16, v154
	v_and_b32_e32 v1, 0xffff0000, v154
	v_lshlrev_b32_e32 v2, 16, v155
	v_and_b32_e32 v3, 0xffff0000, v155
	v_mul_f32_e32 v0, v12, v0
	v_mul_f32_e32 v1, v13, v1
	v_mul_f32_e32 v2, v14, v2
	v_mul_f32_e32 v3, v15, v3
	v_cvt_pk_bf16_f32 v0, v0, v1
	v_cvt_pk_bf16_f32 v1, v2, v3
	v_mfma_f32_32x32x16_bf16 v[16:31], v[126:129], v[64:67], v[16:31]
	v_mov_b32_e32 v186, v0
	v_mov_b32_e32 v187, v1
	s_nop 1
	v_permlane32_swap_b32_e32 v184, v186
	v_permlane32_swap_b32_e32 v185, v187
	global_store_dwordx4 v[180:181], v[184:187], off offset:32
	v_lshlrev_b32_e32 v0, 16, v156
	v_and_b32_e32 v1, 0xffff0000, v156
	v_lshlrev_b32_e32 v2, 16, v157
	v_and_b32_e32 v3, 0xffff0000, v157
	s_nop 5
	v_mul_f32_e32 v0, v16, v0
	v_mul_f32_e32 v1, v17, v1
	v_mul_f32_e32 v2, v18, v2
	v_mul_f32_e32 v3, v19, v3
	v_cvt_pk_bf16_f32 v0, v0, v1
	v_cvt_pk_bf16_f32 v1, v2, v3
	v_mfma_f32_32x32x16_bf16 v[32:47], v[130:133], v[76:79], v[32:47]
	v_mov_b32_e32 v184, v0
	v_mov_b32_e32 v185, v1
	v_lshlrev_b32_e32 v0, 16, v158
	v_and_b32_e32 v1, 0xffff0000, v158
	v_lshlrev_b32_e32 v2, 16, v159
	v_and_b32_e32 v3, 0xffff0000, v159
	v_mul_f32_e32 v0, v20, v0
	v_mul_f32_e32 v1, v21, v1
	v_mul_f32_e32 v2, v22, v2
	v_mul_f32_e32 v3, v23, v3
	v_cvt_pk_bf16_f32 v0, v0, v1
	v_cvt_pk_bf16_f32 v1, v2, v3
	v_mfma_f32_32x32x16_bf16 v[32:47], v[134:137], v[72:75], v[32:47]
	v_mov_b32_e32 v186, v0
	v_mov_b32_e32 v187, v1
	s_nop 1
	v_permlane32_swap_b32_e32 v184, v186
	v_permlane32_swap_b32_e32 v185, v187
	global_store_dwordx4 v[180:181], v[184:187], off offset:64
	v_lshlrev_b32_e32 v0, 16, v160
	v_and_b32_e32 v1, 0xffff0000, v160
	v_lshlrev_b32_e32 v2, 16, v161
	v_and_b32_e32 v3, 0xffff0000, v161
	v_mul_f32_e32 v0, v24, v0
	v_mul_f32_e32 v1, v25, v1
	v_mul_f32_e32 v2, v26, v2
	v_mul_f32_e32 v3, v27, v3
	v_cvt_pk_bf16_f32 v0, v0, v1
	v_cvt_pk_bf16_f32 v1, v2, v3
	v_mfma_f32_32x32x16_bf16 v[32:47], v[80:83], v[68:71], v[32:47]
	v_mov_b32_e32 v184, v0
	v_mov_b32_e32 v185, v1
	v_lshlrev_b32_e32 v0, 16, v162
	v_and_b32_e32 v1, 0xffff0000, v162
	v_lshlrev_b32_e32 v2, 16, v163
	v_and_b32_e32 v3, 0xffff0000, v163
	v_mul_f32_e32 v0, v28, v0
	v_mul_f32_e32 v1, v29, v1
	v_mul_f32_e32 v2, v30, v2
	v_mul_f32_e32 v3, v31, v3
	v_cvt_pk_bf16_f32 v0, v0, v1
	v_cvt_pk_bf16_f32 v1, v2, v3
	v_mfma_f32_32x32x16_bf16 v[32:47], v[98:101], v[64:67], v[32:47]
	v_mov_b32_e32 v186, v0
	v_mov_b32_e32 v187, v1
	s_nop 1
	v_permlane32_swap_b32_e32 v184, v186
	v_permlane32_swap_b32_e32 v185, v187
	global_store_dwordx4 v[180:181], v[184:187], off offset:96
	v_lshlrev_b32_e32 v0, 16, v164
	v_and_b32_e32 v1, 0xffff0000, v164
	v_lshlrev_b32_e32 v2, 16, v165
	v_and_b32_e32 v3, 0xffff0000, v165
	s_nop 5
	v_mul_f32_e32 v0, v32, v0
	v_mul_f32_e32 v1, v33, v1
	v_mul_f32_e32 v2, v34, v2
	v_mul_f32_e32 v3, v35, v3
	v_cvt_pk_bf16_f32 v0, v0, v1
	v_cvt_pk_bf16_f32 v1, v2, v3
	v_mfma_f32_32x32x16_bf16 v[48:63], v[110:113], v[92:95], v[48:63]
	v_mov_b32_e32 v184, v0
	v_mov_b32_e32 v185, v1
	v_lshlrev_b32_e32 v0, 16, v166
	v_and_b32_e32 v1, 0xffff0000, v166
	v_lshlrev_b32_e32 v2, 16, v167
	v_and_b32_e32 v3, 0xffff0000, v167
	v_mul_f32_e32 v0, v36, v0
	v_mul_f32_e32 v1, v37, v1
	v_mul_f32_e32 v2, v38, v2
	v_mul_f32_e32 v3, v39, v3
	v_cvt_pk_bf16_f32 v0, v0, v1
	v_cvt_pk_bf16_f32 v1, v2, v3
	v_mfma_f32_32x32x16_bf16 v[48:63], v[138:141], v[76:79], v[48:63]
	v_mov_b32_e32 v186, v0
	v_mov_b32_e32 v187, v1
	s_nop 1
	v_permlane32_swap_b32_e32 v184, v186
	v_permlane32_swap_b32_e32 v185, v187
	global_store_dwordx4 v[180:181], v[184:187], off offset:128
	v_lshlrev_b32_e32 v0, 16, v168
	v_and_b32_e32 v1, 0xffff0000, v168
	v_lshlrev_b32_e32 v2, 16, v169
	v_and_b32_e32 v3, 0xffff0000, v169
	v_mul_f32_e32 v0, v40, v0
	v_mul_f32_e32 v1, v41, v1
	v_mul_f32_e32 v2, v42, v2
	v_mul_f32_e32 v3, v43, v3
	v_cvt_pk_bf16_f32 v0, v0, v1
	v_cvt_pk_bf16_f32 v1, v2, v3
	v_mfma_f32_32x32x16_bf16 v[48:63], v[142:145], v[72:75], v[48:63]
	v_mov_b32_e32 v184, v0
	v_mov_b32_e32 v185, v1
	v_lshlrev_b32_e32 v0, 16, v170
	v_and_b32_e32 v1, 0xffff0000, v170
	v_lshlrev_b32_e32 v2, 16, v171
	v_and_b32_e32 v3, 0xffff0000, v171
	v_mul_f32_e32 v0, v44, v0
	v_mul_f32_e32 v1, v45, v1
	v_mul_f32_e32 v2, v46, v2
	v_mul_f32_e32 v3, v47, v3
	v_cvt_pk_bf16_f32 v0, v0, v1
	v_cvt_pk_bf16_f32 v1, v2, v3
	v_mfma_f32_32x32x16_bf16 v[48:63], v[84:87], v[68:71], v[48:63]
	v_mov_b32_e32 v186, v0
	v_mov_b32_e32 v187, v1
	s_nop 1
	v_permlane32_swap_b32_e32 v184, v186
	v_permlane32_swap_b32_e32 v185, v187
	global_store_dwordx4 v[180:181], v[184:187], off offset:160
	v_lshlrev_b32_e32 v0, 16, v172
	v_mfma_f32_32x32x16_bf16 v[48:63], v[102:105], v[64:67], v[48:63]
	v_and_b32_e32 v1, 0xffff0000, v172
	v_lshlrev_b32_e32 v2, 16, v173
	v_and_b32_e32 v3, 0xffff0000, v173
	s_nop 8
	v_mul_f32_e32 v0, v48, v0
	v_mul_f32_e32 v1, v49, v1
	v_mul_f32_e32 v2, v50, v2
	v_mul_f32_e32 v3, v51, v3
	v_cvt_pk_bf16_f32 v0, v0, v1
	v_cvt_pk_bf16_f32 v1, v2, v3
	s_nop 0
	v_mov_b32_e32 v184, v0
	v_mov_b32_e32 v185, v1
	v_lshlrev_b32_e32 v0, 16, v174
	v_and_b32_e32 v1, 0xffff0000, v174
	v_lshlrev_b32_e32 v2, 16, v175
	v_and_b32_e32 v3, 0xffff0000, v175
	v_mul_f32_e32 v0, v52, v0
	v_mul_f32_e32 v1, v53, v1
	v_mul_f32_e32 v2, v54, v2
	v_mul_f32_e32 v3, v55, v3
	v_cvt_pk_bf16_f32 v0, v0, v1
	v_cvt_pk_bf16_f32 v1, v2, v3
	s_nop 0
	v_mov_b32_e32 v186, v0
	v_mov_b32_e32 v187, v1
	s_nop 1
	v_permlane32_swap_b32_e32 v184, v186
	v_permlane32_swap_b32_e32 v185, v187
	global_store_dwordx4 v[180:181], v[184:187], off offset:192
	v_lshlrev_b32_e32 v0, 16, v176
	v_and_b32_e32 v1, 0xffff0000, v176
	v_lshlrev_b32_e32 v2, 16, v177
	v_and_b32_e32 v3, 0xffff0000, v177
	v_mul_f32_e32 v0, v56, v0
	v_mul_f32_e32 v1, v57, v1
	v_mul_f32_e32 v2, v58, v2
	v_mul_f32_e32 v3, v59, v3
	v_cvt_pk_bf16_f32 v0, v0, v1
	v_cvt_pk_bf16_f32 v1, v2, v3
	s_nop 0
	v_mov_b32_e32 v184, v0
	v_mov_b32_e32 v185, v1
	v_lshlrev_b32_e32 v0, 16, v178
	v_and_b32_e32 v1, 0xffff0000, v178
	v_lshlrev_b32_e32 v2, 16, v179
	v_and_b32_e32 v3, 0xffff0000, v179
	v_mul_f32_e32 v0, v60, v0
	v_mul_f32_e32 v1, v61, v1
	v_mul_f32_e32 v2, v62, v2
	v_mul_f32_e32 v3, v63, v3
	v_cvt_pk_bf16_f32 v0, v0, v1
	v_cvt_pk_bf16_f32 v1, v2, v3
	v_mov_b32_e32 v186, v0
	v_mov_b32_e32 v187, v1
	s_nop 1
	v_permlane32_swap_b32_e32 v184, v186
	v_permlane32_swap_b32_e32 v185, v187
	global_store_dwordx4 v[180:181], v[184:187], off offset:224
	s_waitcnt lgkmcnt(0)
	s_barrier
	s_cbranch_scc0 .LBB0_548

.LBB0_1084:
	v_mov_b32_e32 v151, v149
	v_lshl_add_u64 v[32:33], s[94:95], 0, v[150:151]
	v_lshlrev_b32_e32 v34, 1, v144
	v_mov_b32_e32 v35, v149
	v_lshl_add_u64 v[32:33], v[32:33], 0, v[34:35]
	global_load_dwordx2 v[34:35], v[32:33], off
	v_bfe_u32 v198, v192, 5, 1
	v_lshlrev_b32_e32 v198, 3, v198
	v_mov_b32_e32 v199, 0
	v_lshl_add_u64 v[198:199], v[32:33], 0, v[198:199]
	v_rcp_f32_e32 v36, v127
	s_waitcnt vmcnt(0)
	v_permlane32_swap_b32_e32 v242, v244
	v_permlane32_swap_b32_e32 v243, v245
	v_permlane32_swap_b32_e32 v246, v248
	v_permlane32_swap_b32_e32 v247, v249
	v_permlane32_swap_b32_e32 v250, v252
	v_permlane32_swap_b32_e32 v251, v253
	s_nop 0
	v_lshlrev_b32_e32 v37, 16, v34
	v_mul_f32_e32 v16, v16, v36
	v_mul_f32_e32 v17, v17, v36
	v_mul_f32_e32 v18, v18, v36
	v_mul_f32_e32 v19, v19, v36
	v_and_b32_e32 v34, 0xffff0000, v34
	v_lshlrev_b32_e32 v38, 16, v35
	v_and_b32_e32 v35, 0xffff0000, v35
	v_mul_f32_e32 v16, v16, v37
	v_mul_f32_e32 v17, v17, v34
	v_mul_f32_e32 v18, v18, v38
	v_mul_f32_e32 v19, v19, v35
	v_cvt_pk_bf16_f32 v16, v16, v17
	v_cvt_pk_bf16_f32 v17, v18, v19
	v_mul_f32_e32 v20, v20, v36
	v_mul_f32_e32 v21, v21, v36
	v_mul_f32_e32 v22, v22, v36
	v_mul_f32_e32 v23, v23, v36
	v_mov_b32_e32 v200, v16
	v_mov_b32_e32 v201, v17
	v_mul_f32_e32 v0, v0, v36
	v_mul_f32_e32 v1, v1, v36
	v_mul_f32_e32 v2, v2, v36
	v_mul_f32_e32 v3, v3, v36
	v_mul_f32_e32 v4, v4, v36
	v_mul_f32_e32 v5, v5, v36
	v_mul_f32_e32 v6, v6, v36
	v_mul_f32_e32 v7, v7, v36
	v_lshlrev_b32_e32 v16, 16, v240
	v_and_b32_e32 v17, 0xffff0000, v240
	v_lshlrev_b32_e32 v18, 16, v241
	v_and_b32_e32 v19, 0xffff0000, v241
	v_mul_f32_e32 v16, v20, v16
	v_mul_f32_e32 v17, v21, v17
	v_mul_f32_e32 v18, v22, v18
	v_mul_f32_e32 v19, v23, v19
	v_cvt_pk_bf16_f32 v16, v16, v17
	v_cvt_pk_bf16_f32 v17, v18, v19
	v_mul_f32_e32 v20, v24, v36
	v_mul_f32_e32 v21, v25, v36
	v_mul_f32_e32 v22, v26, v36
	v_mul_f32_e32 v23, v27, v36
	v_mov_b32_e32 v202, v16
	v_mov_b32_e32 v203, v17
	s_nop 1
	v_permlane32_swap_b32_e32 v200, v202
	v_permlane32_swap_b32_e32 v201, v203
	global_store_dwordx4 v[198:199], v[200:203], off
	v_lshlrev_b32_e32 v16, 16, v242
	v_and_b32_e32 v17, 0xffff0000, v242
	v_lshlrev_b32_e32 v18, 16, v243
	v_and_b32_e32 v19, 0xffff0000, v243
	v_mul_f32_e32 v16, v20, v16
	v_mul_f32_e32 v17, v21, v17
	v_mul_f32_e32 v18, v22, v18
	v_mul_f32_e32 v19, v23, v19
	v_cvt_pk_bf16_f32 v16, v16, v17
	v_cvt_pk_bf16_f32 v17, v18, v19
	v_mul_f32_e32 v20, v28, v36
	v_mul_f32_e32 v21, v29, v36
	v_mul_f32_e32 v22, v30, v36
	v_mul_f32_e32 v23, v31, v36
	v_mov_b32_e32 v200, v16
	v_mov_b32_e32 v201, v17
	v_lshlrev_b32_e32 v16, 16, v244
	v_and_b32_e32 v17, 0xffff0000, v244
	v_lshlrev_b32_e32 v18, 16, v245
	v_and_b32_e32 v19, 0xffff0000, v245
	v_mul_f32_e32 v16, v20, v16
	v_mul_f32_e32 v17, v21, v17
	v_mul_f32_e32 v18, v22, v18
	v_mul_f32_e32 v19, v23, v19
	v_cvt_pk_bf16_f32 v16, v16, v17
	v_cvt_pk_bf16_f32 v17, v18, v19
	s_nop 0
	v_mov_b32_e32 v202, v16
	v_mov_b32_e32 v203, v17
	s_nop 1
	v_permlane32_swap_b32_e32 v200, v202
	v_permlane32_swap_b32_e32 v201, v203
	global_store_dwordx4 v[198:199], v[200:203], off offset:32
	v_lshlrev_b32_e32 v16, 16, v246
	v_and_b32_e32 v17, 0xffff0000, v246
	v_lshlrev_b32_e32 v18, 16, v247
	v_and_b32_e32 v19, 0xffff0000, v247
	v_mul_f32_e32 v0, v0, v16
	v_mul_f32_e32 v1, v1, v17
	v_mul_f32_e32 v2, v2, v18
	v_mul_f32_e32 v3, v3, v19
	v_cvt_pk_bf16_f32 v0, v0, v1
	v_cvt_pk_bf16_f32 v1, v2, v3
	s_nop 0
	v_mov_b32_e32 v200, v0
	v_mov_b32_e32 v201, v1
	v_lshlrev_b32_e32 v0, 16, v248
	v_and_b32_e32 v1, 0xffff0000, v248
	v_lshlrev_b32_e32 v2, 16, v249
	v_and_b32_e32 v3, 0xffff0000, v249
	v_mul_f32_e32 v0, v4, v0
	v_mul_f32_e32 v1, v5, v1
	v_mul_f32_e32 v2, v6, v2
	v_mul_f32_e32 v3, v7, v3
	v_cvt_pk_bf16_f32 v0, v0, v1
	v_cvt_pk_bf16_f32 v1, v2, v3
	v_mul_f32_e32 v4, v8, v36
	v_mul_f32_e32 v5, v9, v36
	v_mul_f32_e32 v6, v10, v36
	v_mul_f32_e32 v7, v11, v36
	v_mov_b32_e32 v202, v0
	v_mov_b32_e32 v203, v1
	s_nop 1
	v_permlane32_swap_b32_e32 v200, v202
	v_permlane32_swap_b32_e32 v201, v203
	global_store_dwordx4 v[198:199], v[200:203], off offset:64
	v_lshlrev_b32_e32 v0, 16, v250
	v_and_b32_e32 v1, 0xffff0000, v250
	v_lshlrev_b32_e32 v2, 16, v251
	v_and_b32_e32 v3, 0xffff0000, v251
	v_mul_f32_e32 v0, v4, v0
	v_mul_f32_e32 v1, v5, v1
	v_mul_f32_e32 v2, v6, v2
	v_mul_f32_e32 v3, v7, v3
	v_cvt_pk_bf16_f32 v0, v0, v1
	v_cvt_pk_bf16_f32 v1, v2, v3
	v_mul_f32_e32 v4, v12, v36
	v_mul_f32_e32 v5, v13, v36
	v_mov_b32_e32 v200, v0
	v_mov_b32_e32 v201, v1
	v_mul_f32_e32 v6, v14, v36
	v_mul_f32_e32 v7, v15, v36
	v_lshlrev_b32_e32 v0, 16, v252
	v_and_b32_e32 v1, 0xffff0000, v252
	v_lshlrev_b32_e32 v2, 16, v253
	v_and_b32_e32 v3, 0xffff0000, v253
	v_mul_f32_e32 v0, v4, v0
	v_mul_f32_e32 v1, v5, v1
	v_mul_f32_e32 v2, v6, v2
	v_mul_f32_e32 v3, v7, v3
	v_cvt_pk_bf16_f32 v0, v0, v1
	v_cvt_pk_bf16_f32 v1, v2, v3
	v_mov_b32_e32 v202, v0
	v_mov_b32_e32 v203, v1
	s_nop 1
	v_permlane32_swap_b32_e32 v200, v202
	v_permlane32_swap_b32_e32 v201, v203
	global_store_dwordx4 v[198:199], v[200:203], off offset:96
	s_barrier

.LBB0_1317:
	v_mov_b32_e32 v204, v150
	v_mov_b32_e32 v205, v149
	v_lshl_add_u64 v[206:207], s[94:95], 0, v[204:205]
	v_lshlrev_b32_e32 v204, 1, v144
	v_lshl_add_u64 v[206:207], v[206:207], 0, v[204:205]
	global_load_dwordx2 v[240:241], v[206:207], off offset:16
	v_bfe_u32 v208, v192, 5, 1
	v_lshlrev_b32_e32 v208, 3, v208
	v_mov_b32_e32 v209, 0
	v_lshl_add_u64 v[208:209], v[206:207], 0, v[208:209]
	global_load_dwordx4 v[242:245], v[208:209], off offset:32
	global_load_dwordx4 v[246:249], v[208:209], off offset:64
	global_load_dwordx4 v[250:253], v[208:209], off offset:96
	s_and_b64 vcc, exec, s[70:71]
	s_cbranch_vccnz .LBB0_1319
	v_exp_f32_e32 v36, v48
	v_add_f32_e32 v33, 0, v166
	v_exp_f32_e32 v37, v49
	v_add_f32_e32 v33, v167, v33
	v_exp_f32_e32 v38, v50
	v_add_f32_e32 v33, v168, v33
	v_exp_f32_e32 v39, v51
	v_add_f32_e32 v33, v169, v33
	v_exp_f32_e32 v40, v52
	v_add_f32_e32 v33, v36, v33
	v_exp_f32_e32 v41, v53
	v_add_f32_e32 v33, v37, v33
	v_exp_f32_e32 v42, v54
	v_add_f32_e32 v33, v38, v33
	v_exp_f32_e32 v43, v55
	v_add_f32_e32 v33, v39, v33
	v_exp_f32_e32 v44, v56
	v_add_f32_e32 v33, v40, v33
	v_exp_f32_e32 v45, v57
	v_add_f32_e32 v33, v41, v33
	v_exp_f32_e32 v46, v58
	v_add_f32_e32 v33, v42, v33
	v_exp_f32_e32 v47, v59
	v_add_f32_e32 v33, v43, v33
	v_exp_f32_e32 v48, v60
	v_add_f32_e32 v33, v44, v33
	v_exp_f32_e32 v49, v61
	v_add_f32_e32 v33, v45, v33
	v_exp_f32_e32 v50, v62
	v_add_f32_e32 v33, v46, v33
	v_exp_f32_e32 v51, v63
	v_add_f32_e32 v33, v47, v33
	v_add_f32_e32 v33, v48, v33
	v_add_f32_e32 v33, v49, v33
	v_add_f32_e32 v33, v50, v33
	v_add_f32_e32 v33, v51, v33
	v_mov_b32_e32 v34, v33
	s_nop 1
	v_permlane32_swap_b32_e32 v33, v34
	v_add_f32_e32 v64, v33, v34
	v_fmac_f32_e32 v64, v176, v32
	v_cvt_pk_bf16_f32 v32, v149, v149
	v_cvt_pk_bf16_f32 v33, v149, v149
	v_cvt_pk_bf16_f32 v34, v166, v167
	v_cvt_pk_bf16_f32 v35, v168, v169
	v_cvt_pk_bf16_f32 v36, v36, v37
	v_cvt_pk_bf16_f32 v37, v38, v39
	v_cvt_pk_bf16_f32 v38, v40, v41
	v_cvt_pk_bf16_f32 v39, v42, v43
	v_cvt_pk_bf16_f32 v40, v44, v45
	v_cvt_pk_bf16_f32 v41, v46, v47
	v_cvt_pk_bf16_f32 v42, v48, v49
	v_cvt_pk_bf16_f32 v43, v50, v51
	ds_read_b64_tr_b16 v[44:45], v185 offset:0
	ds_read_b64_tr_b16 v[46:47], v185 offset:0x400
	ds_read_b64_tr_b16 v[48:49], v185 offset:0x800
	ds_read_b64_tr_b16 v[50:51], v185 offset:0xc00
	ds_read_b64_tr_b16 v[52:53], v185 offset:0x1000
	ds_read_b64_tr_b16 v[54:55], v185 offset:0x1400
	ds_read_b64_tr_b16 v[56:57], v185 offset:0x1800
	ds_read_b64_tr_b16 v[58:59], v185 offset:0x1c00
	s_waitcnt lgkmcnt(0)
	s_mov_b32 s77, s76
	s_mov_b32 s78, s76
	s_mov_b32 s79, s76
	v_mov_b64_e32 v[60:61], s[76:77]
	v_mov_b64_e32 v[62:63], s[78:79]
	s_nop 1
	v_mfma_f32_32x32x16_bf16 v[16:31], v[44:47], v[60:63], v[16:31]
	ds_read_b64_tr_b16 v[44:45], v185 offset:0x200
	ds_read_b64_tr_b16 v[46:47], v185 offset:0x600
	v_mfma_f32_32x32x16_bf16 v[16:31], v[48:51], v[32:35], v[16:31]
	ds_read_b64_tr_b16 v[48:49], v185 offset:0xa00
	ds_read_b64_tr_b16 v[50:51], v185 offset:0xe00
	v_mfma_f32_32x32x16_bf16 v[16:31], v[52:55], v[36:39], v[16:31]
	ds_read_b64_tr_b16 v[52:53], v185 offset:0x1200
	ds_read_b64_tr_b16 v[54:55], v185 offset:0x1600
	v_mfma_f32_32x32x16_bf16 v[16:31], v[56:59], v[40:43], v[16:31]
	ds_read_b64_tr_b16 v[56:57], v185 offset:0x1a00
	ds_read_b64_tr_b16 v[58:59], v185 offset:0x1e00
	s_waitcnt lgkmcnt(0)
	v_mfma_f32_32x32x16_bf16 v[0:15], v[44:47], v[60:63], v[0:15]
	v_mov_b32_e32 v176, v64
	v_mfma_f32_32x32x16_bf16 v[0:15], v[48:51], v[32:35], v[0:15]
	v_mfma_f32_32x32x16_bf16 v[0:15], v[52:55], v[36:39], v[0:15]
	v_mfma_f32_32x32x16_bf16 v[0:15], v[56:59], v[40:43], v[0:15]
.LBB0_1319:
	v_mov_b32_e32 v151, v149
	v_lshl_add_u64 v[32:33], s[94:95], 0, v[150:151]
	v_lshlrev_b32_e32 v34, 1, v144
	v_mov_b32_e32 v35, v149
	v_lshl_add_u64 v[32:33], v[32:33], 0, v[34:35]
	global_load_dwordx2 v[34:35], v[32:33], off
	v_bfe_u32 v198, v192, 5, 1
	v_lshlrev_b32_e32 v198, 3, v198
	v_mov_b32_e32 v199, 0
	v_lshl_add_u64 v[198:199], v[32:33], 0, v[198:199]
	v_rcp_f32_e32 v36, v176
	s_mov_b64 s[70:71], 0
	v_mul_f32_e32 v16, v16, v36
	v_mul_f32_e32 v17, v17, v36
	v_mul_f32_e32 v18, v18, v36
	v_mul_f32_e32 v19, v19, v36
	v_mul_f32_e32 v20, v20, v36
	v_mul_f32_e32 v21, v21, v36
	v_mul_f32_e32 v22, v22, v36
	v_mul_f32_e32 v23, v23, v36
	v_mul_f32_e32 v0, v0, v36
	v_mul_f32_e32 v1, v1, v36
	v_mul_f32_e32 v2, v2, v36
	v_mul_f32_e32 v3, v3, v36
	v_mul_f32_e32 v4, v4, v36
	v_mul_f32_e32 v5, v5, v36
	v_mul_f32_e32 v6, v6, v36
	v_mul_f32_e32 v7, v7, v36
	s_waitcnt vmcnt(0)
	v_permlane32_swap_b32_e32 v242, v244
	v_permlane32_swap_b32_e32 v243, v245
	v_permlane32_swap_b32_e32 v246, v248
	v_permlane32_swap_b32_e32 v247, v249
	v_permlane32_swap_b32_e32 v250, v252
	v_permlane32_swap_b32_e32 v251, v253
	s_nop 0
	v_lshlrev_b32_e32 v37, 16, v34
	v_and_b32_e32 v34, 0xffff0000, v34
	v_lshlrev_b32_e32 v38, 16, v35
	v_and_b32_e32 v35, 0xffff0000, v35
	v_mul_f32_e32 v16, v16, v37
	v_mul_f32_e32 v17, v17, v34
	v_mul_f32_e32 v18, v18, v38
	v_mul_f32_e32 v19, v19, v35
	v_cvt_pk_bf16_f32 v16, v16, v17
	v_cvt_pk_bf16_f32 v17, v18, v19
	s_nop 0
	v_mov_b32_e32 v200, v16
	v_mov_b32_e32 v201, v17
	v_lshlrev_b32_e32 v16, 16, v240
	v_and_b32_e32 v17, 0xffff0000, v240
	v_lshlrev_b32_e32 v18, 16, v241
	v_and_b32_e32 v19, 0xffff0000, v241
	v_mul_f32_e32 v16, v20, v16
	v_mul_f32_e32 v17, v21, v17
	v_mul_f32_e32 v18, v22, v18
	v_mul_f32_e32 v19, v23, v19
	v_cvt_pk_bf16_f32 v16, v16, v17
	v_cvt_pk_bf16_f32 v17, v18, v19
	v_mul_f32_e32 v20, v24, v36
	v_mul_f32_e32 v21, v25, v36
	v_mul_f32_e32 v22, v26, v36
	v_mul_f32_e32 v23, v27, v36
	v_mov_b32_e32 v202, v16
	v_mov_b32_e32 v203, v17
	s_nop 1
	v_permlane32_swap_b32_e32 v200, v202
	v_permlane32_swap_b32_e32 v201, v203
	global_store_dwordx4 v[198:199], v[200:203], off
	v_lshlrev_b32_e32 v16, 16, v242
	v_and_b32_e32 v17, 0xffff0000, v242
	v_lshlrev_b32_e32 v18, 16, v243
	v_and_b32_e32 v19, 0xffff0000, v243
	v_mul_f32_e32 v16, v20, v16
	v_mul_f32_e32 v17, v21, v17
	v_mul_f32_e32 v18, v22, v18
	v_mul_f32_e32 v19, v23, v19
	v_cvt_pk_bf16_f32 v16, v16, v17
	v_cvt_pk_bf16_f32 v17, v18, v19
	v_mul_f32_e32 v20, v28, v36
	v_mul_f32_e32 v21, v29, v36
	v_mul_f32_e32 v22, v30, v36
	v_mul_f32_e32 v23, v31, v36
	v_mov_b32_e32 v200, v16
	v_mov_b32_e32 v201, v17
	v_lshlrev_b32_e32 v16, 16, v244
	v_and_b32_e32 v17, 0xffff0000, v244
	v_lshlrev_b32_e32 v18, 16, v245
	v_and_b32_e32 v19, 0xffff0000, v245
	v_mul_f32_e32 v16, v20, v16
	v_mul_f32_e32 v17, v21, v17
	v_mul_f32_e32 v18, v22, v18
	v_mul_f32_e32 v19, v23, v19
	v_cvt_pk_bf16_f32 v16, v16, v17
	v_cvt_pk_bf16_f32 v17, v18, v19
	s_nop 0
	v_mov_b32_e32 v202, v16
	v_mov_b32_e32 v203, v17
	s_nop 1
	v_permlane32_swap_b32_e32 v200, v202
	v_permlane32_swap_b32_e32 v201, v203
	global_store_dwordx4 v[198:199], v[200:203], off offset:32
	v_lshlrev_b32_e32 v16, 16, v246
	v_and_b32_e32 v17, 0xffff0000, v246
	v_lshlrev_b32_e32 v18, 16, v247
	v_and_b32_e32 v19, 0xffff0000, v247
	v_mul_f32_e32 v0, v0, v16
	v_mul_f32_e32 v1, v1, v17
	v_mul_f32_e32 v2, v2, v18
	v_mul_f32_e32 v3, v3, v19
	v_cvt_pk_bf16_f32 v0, v0, v1
	v_cvt_pk_bf16_f32 v1, v2, v3
	s_nop 0
	v_mov_b32_e32 v200, v0
	v_mov_b32_e32 v201, v1
	v_lshlrev_b32_e32 v0, 16, v248
	v_and_b32_e32 v1, 0xffff0000, v248
	v_lshlrev_b32_e32 v2, 16, v249
	v_and_b32_e32 v3, 0xffff0000, v249
	v_mul_f32_e32 v0, v4, v0
	v_mul_f32_e32 v1, v5, v1
	v_mul_f32_e32 v2, v6, v2
	v_mul_f32_e32 v3, v7, v3
	v_cvt_pk_bf16_f32 v0, v0, v1
	v_cvt_pk_bf16_f32 v1, v2, v3
	v_mul_f32_e32 v4, v8, v36
	v_mul_f32_e32 v5, v9, v36
	v_mul_f32_e32 v6, v10, v36
	v_mul_f32_e32 v7, v11, v36
	v_mov_b32_e32 v202, v0
	v_mov_b32_e32 v203, v1
	s_nop 1
	v_permlane32_swap_b32_e32 v200, v202
	v_permlane32_swap_b32_e32 v201, v203
	global_store_dwordx4 v[198:199], v[200:203], off offset:64
	v_lshlrev_b32_e32 v0, 16, v250
	v_and_b32_e32 v1, 0xffff0000, v250
	v_lshlrev_b32_e32 v2, 16, v251
	v_and_b32_e32 v3, 0xffff0000, v251
	v_mul_f32_e32 v0, v4, v0
	v_mul_f32_e32 v1, v5, v1
	v_mul_f32_e32 v2, v6, v2
	v_mul_f32_e32 v3, v7, v3
	v_cvt_pk_bf16_f32 v0, v0, v1
	v_cvt_pk_bf16_f32 v1, v2, v3
	v_mul_f32_e32 v4, v12, v36
	v_mul_f32_e32 v5, v13, v36
	v_mov_b32_e32 v200, v0
	v_mov_b32_e32 v201, v1
	v_mul_f32_e32 v6, v14, v36
	v_mul_f32_e32 v7, v15, v36
	v_lshlrev_b32_e32 v0, 16, v252
	v_and_b32_e32 v1, 0xffff0000, v252
	v_lshlrev_b32_e32 v2, 16, v253
	v_and_b32_e32 v3, 0xffff0000, v253
	v_mul_f32_e32 v0, v4, v0
	v_mul_f32_e32 v1, v5, v1
	v_mul_f32_e32 v2, v6, v2
	v_mul_f32_e32 v3, v7, v3
	v_cvt_pk_bf16_f32 v0, v0, v1
	v_cvt_pk_bf16_f32 v1, v2, v3
	v_mov_b32_e32 v202, v0
	v_mov_b32_e32 v203, v1
	s_nop 1
	v_permlane32_swap_b32_e32 v200, v202
	v_permlane32_swap_b32_e32 v201, v203
	global_store_dwordx4 v[198:199], v[200:203], off offset:96
	s_barrier

.LBB0_1545:
	v_mov_b32_e32 v204, v150
	v_mov_b32_e32 v205, v149
	v_lshl_add_u64 v[206:207], s[94:95], 0, v[204:205]
	v_lshlrev_b32_e32 v204, 1, v144
	v_lshl_add_u64 v[206:207], v[206:207], 0, v[204:205]
	global_load_dwordx2 v[240:241], v[206:207], off offset:16
	v_bfe_u32 v208, v192, 5, 1
	v_lshlrev_b32_e32 v208, 3, v208
	v_mov_b32_e32 v209, 0
	v_lshl_add_u64 v[208:209], v[206:207], 0, v[208:209]
	global_load_dwordx4 v[242:245], v[208:209], off offset:32
	global_load_dwordx4 v[246:249], v[208:209], off offset:64
	global_load_dwordx4 v[250:253], v[208:209], off offset:96
	s_and_b64 vcc, exec, s[70:71]
	s_cbranch_vccnz .LBB0_1084
	v_add_f32_e32 v33, 0, v142
	v_add_f32_e32 v33, v143, v33
	v_add_f32_e32 v33, v160, v33
	v_add_f32_e32 v33, v161, v33
	v_add_f32_e32 v33, v164, v33
	v_add_f32_e32 v33, v165, v33
	v_add_f32_e32 v33, v166, v33
	v_add_f32_e32 v33, v167, v33
	v_add_f32_e32 v33, v168, v33
	v_add_f32_e32 v33, v169, v33
	v_add_f32_e32 v33, v170, v33
	v_add_f32_e32 v33, v171, v33
	v_exp_f32_e32 v40, v34
	v_add_f32_e32 v33, v172, v33
	v_exp_f32_e32 v41, v35
	v_add_f32_e32 v33, v173, v33
	v_exp_f32_e32 v42, v162
	v_add_f32_e32 v33, v174, v33
	v_exp_f32_e32 v43, v163
	v_add_f32_e32 v33, v175, v33
	v_add_f32_e32 v33, v40, v33
	v_add_f32_e32 v33, v41, v33
	v_add_f32_e32 v33, v42, v33
	v_add_f32_e32 v33, v43, v33
	v_mov_b32_e32 v34, v33
	s_nop 1
	v_permlane32_swap_b32_e32 v33, v34
	v_add_f32_e32 v64, v33, v34
	v_fmac_f32_e32 v64, v127, v32
	v_cvt_pk_bf16_f32 v32, v142, v143
	v_cvt_pk_bf16_f32 v33, v160, v161
	v_cvt_pk_bf16_f32 v34, v164, v165
	v_cvt_pk_bf16_f32 v35, v166, v167
	v_cvt_pk_bf16_f32 v36, v168, v169
	v_cvt_pk_bf16_f32 v37, v170, v171
	v_cvt_pk_bf16_f32 v38, v172, v173
	v_cvt_pk_bf16_f32 v39, v174, v175
	v_cvt_pk_bf16_f32 v40, v40, v41
	v_cvt_pk_bf16_f32 v41, v42, v43
	v_cvt_pk_bf16_f32 v42, v149, v149
	v_cvt_pk_bf16_f32 v43, v149, v149
	ds_read_b64_tr_b16 v[44:45], v185 offset:0
	ds_read_b64_tr_b16 v[46:47], v185 offset:0x400
	ds_read_b64_tr_b16 v[48:49], v185 offset:0x800
	ds_read_b64_tr_b16 v[50:51], v185 offset:0xc00
	ds_read_b64_tr_b16 v[52:53], v185 offset:0x1000
	ds_read_b64_tr_b16 v[54:55], v185 offset:0x1400
	ds_read_b64_tr_b16 v[56:57], v185 offset:0x1800
	ds_read_b64_tr_b16 v[58:59], v185 offset:0x1c00
	s_waitcnt lgkmcnt(0)
	s_nop 0
	v_mfma_f32_32x32x16_bf16 v[16:31], v[44:47], v[32:35], v[16:31]
	s_mov_b32 s77, s76
	s_mov_b32 s78, s76
	s_mov_b32 s79, s76
	v_mov_b64_e32 v[44:45], s[76:77]
	v_mov_b64_e32 v[46:47], s[78:79]
	v_mfma_f32_32x32x16_bf16 v[16:31], v[48:51], v[36:39], v[16:31]
	ds_read_b64_tr_b16 v[48:49], v185 offset:0x200
	ds_read_b64_tr_b16 v[50:51], v185 offset:0x600
	v_mfma_f32_32x32x16_bf16 v[16:31], v[52:55], v[40:43], v[16:31]
	ds_read_b64_tr_b16 v[52:53], v185 offset:0xa00
	ds_read_b64_tr_b16 v[54:55], v185 offset:0xe00
	v_mfma_f32_32x32x16_bf16 v[16:31], v[56:59], v[44:47], v[16:31]
	ds_read_b64_tr_b16 v[56:57], v185 offset:0x1200
	ds_read_b64_tr_b16 v[58:59], v185 offset:0x1600
	ds_read_b64_tr_b16 v[60:61], v185 offset:0x1a00
	ds_read_b64_tr_b16 v[62:63], v185 offset:0x1e00
	s_waitcnt lgkmcnt(0)
	v_mfma_f32_32x32x16_bf16 v[0:15], v[48:51], v[32:35], v[0:15]
	v_mov_b32_e32 v127, v64
	v_mfma_f32_32x32x16_bf16 v[0:15], v[52:55], v[36:39], v[0:15]
	v_mfma_f32_32x32x16_bf16 v[0:15], v[56:59], v[40:43], v[0:15]
	v_mfma_f32_32x32x16_bf16 v[0:15], v[60:63], v[44:47], v[0:15]
	s_branch .LBB0_1084

.LBB0_1559:
	v_exp_f32_e32 v52, v64
	v_exp_f32_e32 v53, v65
	v_exp_f32_e32 v54, v66
	v_exp_f32_e32 v55, v67
	v_exp_f32_e32 v56, v68
	v_add_f32_e32 v49, v49, v50
	v_exp_f32_e32 v50, v32
	v_add_f32_e32 v32, 0, v52
	v_exp_f32_e32 v57, v69
	v_add_f32_e32 v32, v53, v32
	v_exp_f32_e32 v58, v70
	v_add_f32_e32 v32, v54, v32
	v_exp_f32_e32 v59, v71
	v_add_f32_e32 v32, v55, v32
	v_exp_f32_e32 v60, v72
	v_add_f32_e32 v32, v56, v32
	v_sub_f32_e32 v51, 0xf149f2ca, v111
	v_exp_f32_e32 v61, v73
	v_add_f32_e32 v32, v57, v32
	v_exp_f32_e32 v51, v51
	v_exp_f32_e32 v62, v74
	v_add_f32_e32 v32, v58, v32
	v_exp_f32_e32 v63, v75
	v_add_f32_e32 v32, v59, v32
	v_exp_f32_e32 v64, v76
	v_add_f32_e32 v32, v60, v32
	v_exp_f32_e32 v65, v77
	v_add_f32_e32 v32, v61, v32
	v_exp_f32_e32 v66, v78
	v_mul_f32_e32 v51, 0, v51
	v_add_f32_e32 v32, v62, v32
	v_exp_f32_e32 v67, v79
	v_add_f32_e32 v68, v115, v119
	v_cndmask_b32_e64 v51, v51, 0, s[2:3]
	v_add_f32_e32 v32, v63, v32
	v_add_f32_e32 v51, v51, v68
	v_add_f32_e32 v68, v121, v122
	v_add_f32_e32 v32, v64, v32
	v_fmac_f32_e32 v68, v51, v106
	v_exp_f32_e32 v51, v33
	v_add_f32_e32 v32, v65, v32
	v_fmac_f32_e32 v49, v68, v118
	v_exp_f32_e32 v68, v34
	v_add_f32_e32 v32, v66, v32
	v_exp_f32_e32 v69, v35
	v_add_f32_e32 v32, v67, v32
	v_exp_f32_e32 v70, v36
	v_add_f32_e32 v32, v50, v32
	v_exp_f32_e32 v71, v37
	v_add_f32_e32 v32, v51, v32
	v_exp_f32_e32 v72, v38
	v_add_f32_e32 v32, v68, v32
	v_exp_f32_e32 v73, v39
	v_add_f32_e32 v32, v69, v32
	v_exp_f32_e32 v74, v40
	v_add_f32_e32 v32, v70, v32
	v_exp_f32_e32 v75, v41
	v_add_f32_e32 v32, v71, v32
	v_exp_f32_e32 v76, v42
	v_add_f32_e32 v32, v72, v32
	v_exp_f32_e32 v77, v43
	v_add_f32_e32 v32, v73, v32
	v_exp_f32_e32 v78, v44
	v_add_f32_e32 v32, v74, v32
	v_exp_f32_e32 v79, v45
	v_add_f32_e32 v32, v75, v32
	v_exp_f32_e32 v80, v46
	v_add_f32_e32 v32, v76, v32
	v_exp_f32_e32 v47, v47
	v_add_f32_e32 v32, v77, v32
	v_add_f32_e32 v32, v78, v32
	v_add_f32_e32 v32, v79, v32
	v_add_f32_e32 v32, v80, v32
	v_add_f32_e32 v32, v47, v32
	v_mov_b32_e32 v33, v32
	s_nop 1
	v_permlane32_swap_b32_e32 v32, v33
	v_add_f32_e32 v81, v32, v33
	v_fmac_f32_e32 v81, v49, v48
	v_cvt_pk_bf16_f32 v32, v52, v53
	v_cvt_pk_bf16_f32 v33, v54, v55
	v_cvt_pk_bf16_f32 v34, v56, v57
	v_cvt_pk_bf16_f32 v35, v58, v59
	v_cvt_pk_bf16_f32 v36, v60, v61
	v_cvt_pk_bf16_f32 v37, v62, v63
	v_cvt_pk_bf16_f32 v38, v64, v65
	v_cvt_pk_bf16_f32 v39, v66, v67
	v_cvt_pk_bf16_f32 v40, v50, v51
	v_cvt_pk_bf16_f32 v41, v68, v69
	v_cvt_pk_bf16_f32 v42, v70, v71
	v_cvt_pk_bf16_f32 v43, v72, v73
	v_cvt_pk_bf16_f32 v44, v74, v75
	v_cvt_pk_bf16_f32 v45, v76, v77
	v_cvt_pk_bf16_f32 v46, v78, v79
	v_cvt_pk_bf16_f32 v47, v80, v47
	ds_read_b64_tr_b16 v[48:49], v125 offset:0
	ds_read_b64_tr_b16 v[50:51], v125 offset:0x400
	ds_read_b64_tr_b16 v[52:53], v125 offset:0x800
	ds_read_b64_tr_b16 v[54:55], v125 offset:0xc00
	ds_read_b64_tr_b16 v[56:57], v125 offset:0x1000
	ds_read_b64_tr_b16 v[58:59], v125 offset:0x1400
	ds_read_b64_tr_b16 v[60:61], v125 offset:0x1800
	ds_read_b64_tr_b16 v[62:63], v125 offset:0x1c00
	s_waitcnt lgkmcnt(0)
	s_nop 0
	v_mfma_f32_32x32x16_bf16 v[16:31], v[48:51], v[32:35], v[16:31]
	ds_read_b64_tr_b16 v[48:49], v125 offset:0x200
	ds_read_b64_tr_b16 v[50:51], v125 offset:0x600
	v_mfma_f32_32x32x16_bf16 v[16:31], v[52:55], v[36:39], v[16:31]
	ds_read_b64_tr_b16 v[52:53], v125 offset:0xa00
	ds_read_b64_tr_b16 v[54:55], v125 offset:0xe00
	v_mfma_f32_32x32x16_bf16 v[16:31], v[56:59], v[40:43], v[16:31]
	ds_read_b64_tr_b16 v[56:57], v125 offset:0x1200
	ds_read_b64_tr_b16 v[58:59], v125 offset:0x1600
	ds_read_b64_tr_b16 v[64:65], v125 offset:0x1a00
	ds_read_b64_tr_b16 v[66:67], v125 offset:0x1e00
	s_waitcnt lgkmcnt(0)
	v_mfma_f32_32x32x16_bf16 v[16:31], v[60:63], v[44:47], v[16:31]
	v_lshlrev_b32_e32 v106, 1, v104
	v_lshl_add_u64 v[60:61], s[0:1], 0, v[106:107]
	v_lshlrev_b32_e32 v106, 1, v144
	v_lshl_add_u64 v[60:61], v[60:61], 0, v[106:107]
	global_load_dwordx2 v[62:63], v[60:61], off
	v_bfe_u32 v198, v192, 5, 1
	v_lshlrev_b32_e32 v198, 3, v198
	v_mov_b32_e32 v199, 0
	v_lshl_add_u64 v[198:199], v[60:61], 0, v[198:199]
	global_load_dwordx2 v[240:241], v[60:61], off offset:16
	global_load_dwordx4 v[242:245], v[198:199], off offset:32
	global_load_dwordx4 v[246:249], v[198:199], off offset:64
	global_load_dwordx4 v[250:253], v[198:199], off offset:96
	v_rcp_f32_e32 v68, v81
	v_mfma_f32_32x32x16_bf16 v[0:15], v[48:51], v[32:35], v[0:15]
	s_nop 4
	v_mul_f32_e32 v16, v68, v16
	v_mul_f32_e32 v17, v68, v17
	v_mul_f32_e32 v18, v68, v18
	v_mul_f32_e32 v19, v68, v19
	v_mul_f32_e32 v20, v68, v20
	v_mul_f32_e32 v21, v68, v21
	v_mul_f32_e32 v22, v68, v22
	v_mul_f32_e32 v23, v68, v23
	v_mfma_f32_32x32x16_bf16 v[0:15], v[52:55], v[36:39], v[0:15]
	s_waitcnt vmcnt(0)
	v_permlane32_swap_b32_e32 v242, v244
	v_permlane32_swap_b32_e32 v243, v245
	v_permlane32_swap_b32_e32 v246, v248
	v_permlane32_swap_b32_e32 v247, v249
	v_permlane32_swap_b32_e32 v250, v252
	v_permlane32_swap_b32_e32 v251, v253
	s_nop 0
	v_lshlrev_b32_e32 v69, 16, v62
	v_and_b32_e32 v62, 0xffff0000, v62
	v_lshlrev_b32_e32 v70, 16, v63
	v_and_b32_e32 v63, 0xffff0000, v63
	v_mul_f32_e32 v16, v16, v69
	v_mul_f32_e32 v17, v17, v62
	v_mul_f32_e32 v18, v18, v70
	v_mul_f32_e32 v19, v19, v63
	v_cvt_pk_bf16_f32 v16, v16, v17
	v_cvt_pk_bf16_f32 v17, v18, v19
	v_mfma_f32_32x32x16_bf16 v[0:15], v[56:59], v[40:43], v[0:15]
	v_mov_b32_e32 v200, v16
	v_mov_b32_e32 v201, v17
	v_lshlrev_b32_e32 v16, 16, v240
	v_and_b32_e32 v17, 0xffff0000, v240
	v_lshlrev_b32_e32 v18, 16, v241
	v_and_b32_e32 v19, 0xffff0000, v241
	v_mul_f32_e32 v16, v20, v16
	v_mul_f32_e32 v17, v21, v17
	v_mul_f32_e32 v18, v22, v18
	v_mul_f32_e32 v19, v23, v19
	v_cvt_pk_bf16_f32 v16, v16, v17
	v_cvt_pk_bf16_f32 v17, v18, v19
	v_mul_f32_e32 v20, v68, v24
	v_mul_f32_e32 v21, v68, v25
	v_mul_f32_e32 v22, v68, v26
	v_mul_f32_e32 v23, v68, v27
	v_mov_b32_e32 v202, v16
	v_mov_b32_e32 v203, v17
	s_nop 1
	v_permlane32_swap_b32_e32 v200, v202
	v_permlane32_swap_b32_e32 v201, v203
	global_store_dwordx4 v[198:199], v[200:203], off
	v_mfma_f32_32x32x16_bf16 v[0:15], v[64:67], v[44:47], v[0:15]
	v_lshlrev_b32_e32 v16, 16, v242
	v_and_b32_e32 v17, 0xffff0000, v242
	v_lshlrev_b32_e32 v18, 16, v243
	v_and_b32_e32 v19, 0xffff0000, v243
	v_mul_f32_e32 v16, v20, v16
	v_mul_f32_e32 v17, v21, v17
	v_mul_f32_e32 v18, v22, v18
	v_mul_f32_e32 v19, v23, v19
	v_cvt_pk_bf16_f32 v16, v16, v17
	v_cvt_pk_bf16_f32 v17, v18, v19
	v_mul_f32_e32 v20, v68, v28
	v_mul_f32_e32 v21, v68, v29
	v_mul_f32_e32 v22, v68, v30
	v_mul_f32_e32 v23, v68, v31
	v_mov_b32_e32 v200, v16
	v_mov_b32_e32 v201, v17
	v_mul_f32_e32 v0, v68, v0
	v_mul_f32_e32 v1, v68, v1
	v_mul_f32_e32 v2, v68, v2
	v_mul_f32_e32 v3, v68, v3
	v_mul_f32_e32 v4, v68, v4
	v_mul_f32_e32 v5, v68, v5
	v_mul_f32_e32 v6, v68, v6
	v_mul_f32_e32 v7, v68, v7
	v_lshlrev_b32_e32 v16, 16, v244
	v_and_b32_e32 v17, 0xffff0000, v244
	v_lshlrev_b32_e32 v18, 16, v245
	v_and_b32_e32 v19, 0xffff0000, v245
	v_mul_f32_e32 v16, v20, v16
	v_mul_f32_e32 v17, v21, v17
	v_mul_f32_e32 v18, v22, v18
	v_mul_f32_e32 v19, v23, v19
	v_cvt_pk_bf16_f32 v16, v16, v17
	v_cvt_pk_bf16_f32 v17, v18, v19
	s_nop 0
	v_mov_b32_e32 v202, v16
	v_mov_b32_e32 v203, v17
	s_nop 1
	v_permlane32_swap_b32_e32 v200, v202
	v_permlane32_swap_b32_e32 v201, v203
	global_store_dwordx4 v[198:199], v[200:203], off offset:32
	v_lshlrev_b32_e32 v16, 16, v246
	v_and_b32_e32 v17, 0xffff0000, v246
	v_lshlrev_b32_e32 v18, 16, v247
	v_and_b32_e32 v19, 0xffff0000, v247
	v_mul_f32_e32 v0, v0, v16
	v_mul_f32_e32 v1, v1, v17
	v_mul_f32_e32 v2, v2, v18
	v_mul_f32_e32 v3, v3, v19
	v_cvt_pk_bf16_f32 v0, v0, v1
	v_cvt_pk_bf16_f32 v1, v2, v3
	s_nop 0
	v_mov_b32_e32 v200, v0
	v_mov_b32_e32 v201, v1
	v_lshlrev_b32_e32 v0, 16, v248
	v_and_b32_e32 v1, 0xffff0000, v248
	v_lshlrev_b32_e32 v2, 16, v249
	v_and_b32_e32 v3, 0xffff0000, v249
	v_mul_f32_e32 v0, v4, v0
	v_mul_f32_e32 v1, v5, v1
	v_mul_f32_e32 v2, v6, v2
	v_mul_f32_e32 v3, v7, v3
	v_cvt_pk_bf16_f32 v0, v0, v1
	v_cvt_pk_bf16_f32 v1, v2, v3
	v_mul_f32_e32 v4, v68, v8
	v_mul_f32_e32 v5, v68, v9
	v_mul_f32_e32 v6, v68, v10
	v_mul_f32_e32 v7, v68, v11
	v_mov_b32_e32 v202, v0
	v_mov_b32_e32 v203, v1
	s_nop 1
	v_permlane32_swap_b32_e32 v200, v202
	v_permlane32_swap_b32_e32 v201, v203
	global_store_dwordx4 v[198:199], v[200:203], off offset:64
	v_lshlrev_b32_e32 v0, 16, v250
	v_and_b32_e32 v1, 0xffff0000, v250
	v_lshlrev_b32_e32 v2, 16, v251
	v_and_b32_e32 v3, 0xffff0000, v251
	v_mul_f32_e32 v0, v4, v0
	v_mul_f32_e32 v1, v5, v1
	v_mul_f32_e32 v2, v6, v2
	v_mul_f32_e32 v3, v7, v3
	v_cvt_pk_bf16_f32 v0, v0, v1
	v_cvt_pk_bf16_f32 v1, v2, v3
	v_mul_f32_e32 v4, v68, v12
	v_mul_f32_e32 v5, v68, v13
	v_mov_b32_e32 v200, v0
	v_mov_b32_e32 v201, v1
	v_mul_f32_e32 v6, v68, v14
	v_mul_f32_e32 v7, v68, v15
	v_lshlrev_b32_e32 v0, 16, v252
	v_and_b32_e32 v1, 0xffff0000, v252
	v_lshlrev_b32_e32 v2, 16, v253
	v_and_b32_e32 v3, 0xffff0000, v253
	v_mul_f32_e32 v0, v4, v0
	v_mul_f32_e32 v1, v5, v1
	v_mul_f32_e32 v2, v6, v2
	v_mul_f32_e32 v3, v7, v3
	v_cvt_pk_bf16_f32 v0, v0, v1
	v_cvt_pk_bf16_f32 v1, v2, v3
	v_mov_b32_e32 v202, v0
	v_mov_b32_e32 v203, v1
	s_nop 1
	v_permlane32_swap_b32_e32 v200, v202
	v_permlane32_swap_b32_e32 v201, v203
	global_store_dwordx4 v[198:199], v[200:203], off offset:96
	s_barrier

.LBB0_1571:
	v_exp_f32_e32 v52, v64
	v_exp_f32_e32 v53, v65
	v_exp_f32_e32 v54, v66
	v_exp_f32_e32 v55, v67
	v_exp_f32_e32 v56, v68
	v_add_f32_e32 v49, v49, v50
	v_exp_f32_e32 v50, v32
	v_add_f32_e32 v32, 0, v52
	v_exp_f32_e32 v57, v69
	v_add_f32_e32 v32, v53, v32
	v_exp_f32_e32 v58, v70
	v_add_f32_e32 v32, v54, v32
	v_exp_f32_e32 v59, v71
	v_add_f32_e32 v32, v55, v32
	v_exp_f32_e32 v60, v72
	v_add_f32_e32 v32, v56, v32
	v_sub_f32_e32 v51, 0xf149f2ca, v111
	v_exp_f32_e32 v61, v73
	v_add_f32_e32 v32, v57, v32
	v_exp_f32_e32 v51, v51
	v_exp_f32_e32 v62, v74
	v_add_f32_e32 v32, v58, v32
	v_exp_f32_e32 v63, v75
	v_add_f32_e32 v32, v59, v32
	v_exp_f32_e32 v64, v76
	v_add_f32_e32 v32, v60, v32
	v_exp_f32_e32 v65, v77
	v_add_f32_e32 v32, v61, v32
	v_exp_f32_e32 v66, v78
	v_mul_f32_e32 v51, 0, v51
	v_add_f32_e32 v32, v62, v32
	v_exp_f32_e32 v67, v79
	v_add_f32_e32 v68, v115, v133
	v_cndmask_b32_e64 v51, v51, 0, s[2:3]
	v_add_f32_e32 v32, v63, v32
	v_add_f32_e32 v51, v51, v68
	v_add_f32_e32 v68, v135, v136
	v_add_f32_e32 v32, v64, v32
	v_fmac_f32_e32 v68, v51, v106
	v_exp_f32_e32 v51, v33
	v_add_f32_e32 v32, v65, v32
	v_fmac_f32_e32 v49, v68, v124
	v_exp_f32_e32 v68, v34
	v_add_f32_e32 v32, v66, v32
	v_exp_f32_e32 v69, v35
	v_add_f32_e32 v32, v67, v32
	v_exp_f32_e32 v70, v36
	v_add_f32_e32 v32, v50, v32
	v_exp_f32_e32 v71, v37
	v_add_f32_e32 v32, v51, v32
	v_exp_f32_e32 v72, v38
	v_add_f32_e32 v32, v68, v32
	v_exp_f32_e32 v73, v39
	v_add_f32_e32 v32, v69, v32
	v_exp_f32_e32 v74, v40
	v_add_f32_e32 v32, v70, v32
	v_exp_f32_e32 v75, v41
	v_add_f32_e32 v32, v71, v32
	v_exp_f32_e32 v76, v42
	v_add_f32_e32 v32, v72, v32
	v_exp_f32_e32 v77, v43
	v_add_f32_e32 v32, v73, v32
	v_exp_f32_e32 v78, v44
	v_add_f32_e32 v32, v74, v32
	v_exp_f32_e32 v79, v45
	v_add_f32_e32 v32, v75, v32
	v_exp_f32_e32 v80, v46
	v_add_f32_e32 v32, v76, v32
	v_exp_f32_e32 v47, v47
	v_add_f32_e32 v32, v77, v32
	v_add_f32_e32 v32, v78, v32
	v_add_f32_e32 v32, v79, v32
	v_add_f32_e32 v32, v80, v32
	v_add_f32_e32 v32, v47, v32
	v_mov_b32_e32 v33, v32
	s_nop 1
	v_permlane32_swap_b32_e32 v32, v33
	v_add_f32_e32 v81, v32, v33
	v_fmac_f32_e32 v81, v49, v48
	v_cvt_pk_bf16_f32 v32, v52, v53
	v_cvt_pk_bf16_f32 v33, v54, v55
	v_cvt_pk_bf16_f32 v34, v56, v57
	v_cvt_pk_bf16_f32 v35, v58, v59
	v_cvt_pk_bf16_f32 v36, v60, v61
	v_cvt_pk_bf16_f32 v37, v62, v63
	v_cvt_pk_bf16_f32 v38, v64, v65
	v_cvt_pk_bf16_f32 v39, v66, v67
	v_cvt_pk_bf16_f32 v40, v50, v51
	v_cvt_pk_bf16_f32 v41, v68, v69
	v_cvt_pk_bf16_f32 v42, v70, v71
	v_cvt_pk_bf16_f32 v43, v72, v73
	v_cvt_pk_bf16_f32 v44, v74, v75
	v_cvt_pk_bf16_f32 v45, v76, v77
	v_cvt_pk_bf16_f32 v46, v78, v79
	v_cvt_pk_bf16_f32 v47, v80, v47
	ds_read_b64_tr_b16 v[48:49], v125 offset:0
	ds_read_b64_tr_b16 v[50:51], v125 offset:0x400
	ds_read_b64_tr_b16 v[52:53], v125 offset:0x800
	ds_read_b64_tr_b16 v[54:55], v125 offset:0xc00
	ds_read_b64_tr_b16 v[56:57], v125 offset:0x1000
	ds_read_b64_tr_b16 v[58:59], v125 offset:0x1400
	ds_read_b64_tr_b16 v[60:61], v125 offset:0x1800
	ds_read_b64_tr_b16 v[62:63], v125 offset:0x1c00
	s_waitcnt lgkmcnt(0)
	s_nop 0
	v_mfma_f32_32x32x16_bf16 v[16:31], v[48:51], v[32:35], v[16:31]
	ds_read_b64_tr_b16 v[48:49], v125 offset:0x200
	ds_read_b64_tr_b16 v[50:51], v125 offset:0x600
	v_mfma_f32_32x32x16_bf16 v[16:31], v[52:55], v[36:39], v[16:31]
	ds_read_b64_tr_b16 v[52:53], v125 offset:0xa00
	ds_read_b64_tr_b16 v[54:55], v125 offset:0xe00
	v_mfma_f32_32x32x16_bf16 v[16:31], v[56:59], v[40:43], v[16:31]
	ds_read_b64_tr_b16 v[56:57], v125 offset:0x1200
	ds_read_b64_tr_b16 v[58:59], v125 offset:0x1600
	ds_read_b64_tr_b16 v[64:65], v125 offset:0x1a00
	ds_read_b64_tr_b16 v[66:67], v125 offset:0x1e00
	s_waitcnt lgkmcnt(0)
	v_mfma_f32_32x32x16_bf16 v[16:31], v[60:63], v[44:47], v[16:31]
	v_lshlrev_b32_e32 v106, 1, v104
	v_lshl_add_u64 v[60:61], s[0:1], 0, v[106:107]
	v_lshlrev_b32_e32 v106, 1, v144
	v_lshl_add_u64 v[60:61], v[60:61], 0, v[106:107]
	global_load_dwordx2 v[62:63], v[60:61], off
	v_bfe_u32 v198, v192, 5, 1
	v_lshlrev_b32_e32 v198, 3, v198
	v_mov_b32_e32 v199, 0
	v_lshl_add_u64 v[198:199], v[60:61], 0, v[198:199]
	global_load_dwordx2 v[240:241], v[60:61], off offset:16
	global_load_dwordx4 v[242:245], v[198:199], off offset:32
	global_load_dwordx4 v[246:249], v[198:199], off offset:64
	global_load_dwordx4 v[250:253], v[198:199], off offset:96
	v_rcp_f32_e32 v68, v81
	v_mfma_f32_32x32x16_bf16 v[0:15], v[48:51], v[32:35], v[0:15]
	s_mov_b64 s[2:3], 0
	s_nop 3
	v_mul_f32_e32 v16, v68, v16
	v_mul_f32_e32 v17, v68, v17
	v_mul_f32_e32 v18, v68, v18
	v_mul_f32_e32 v19, v68, v19
	v_mul_f32_e32 v20, v68, v20
	v_mul_f32_e32 v21, v68, v21
	v_mul_f32_e32 v22, v68, v22
	v_mul_f32_e32 v23, v68, v23
	v_mfma_f32_32x32x16_bf16 v[0:15], v[52:55], v[36:39], v[0:15]
	s_waitcnt vmcnt(0)
	v_permlane32_swap_b32_e32 v242, v244
	v_permlane32_swap_b32_e32 v243, v245
	v_permlane32_swap_b32_e32 v246, v248
	v_permlane32_swap_b32_e32 v247, v249
	v_permlane32_swap_b32_e32 v250, v252
	v_permlane32_swap_b32_e32 v251, v253
	s_nop 0
	v_lshlrev_b32_e32 v69, 16, v62
	v_and_b32_e32 v62, 0xffff0000, v62
	v_lshlrev_b32_e32 v70, 16, v63
	v_and_b32_e32 v63, 0xffff0000, v63
	v_mul_f32_e32 v16, v16, v69
	v_mul_f32_e32 v17, v17, v62
	v_mul_f32_e32 v18, v18, v70
	v_mul_f32_e32 v19, v19, v63
	v_cvt_pk_bf16_f32 v16, v16, v17
	v_cvt_pk_bf16_f32 v17, v18, v19
	v_mfma_f32_32x32x16_bf16 v[0:15], v[56:59], v[40:43], v[0:15]
	v_mov_b32_e32 v200, v16
	v_mov_b32_e32 v201, v17
	v_lshlrev_b32_e32 v16, 16, v240
	v_and_b32_e32 v17, 0xffff0000, v240
	v_lshlrev_b32_e32 v18, 16, v241
	v_and_b32_e32 v19, 0xffff0000, v241
	v_mul_f32_e32 v16, v20, v16
	v_mul_f32_e32 v17, v21, v17
	v_mul_f32_e32 v18, v22, v18
	v_mul_f32_e32 v19, v23, v19
	v_cvt_pk_bf16_f32 v16, v16, v17
	v_cvt_pk_bf16_f32 v17, v18, v19
	v_mul_f32_e32 v20, v68, v24
	v_mul_f32_e32 v21, v68, v25
	v_mul_f32_e32 v22, v68, v26
	v_mul_f32_e32 v23, v68, v27
	v_mov_b32_e32 v202, v16
	v_mov_b32_e32 v203, v17
	s_nop 1
	v_permlane32_swap_b32_e32 v200, v202
	v_permlane32_swap_b32_e32 v201, v203
	global_store_dwordx4 v[198:199], v[200:203], off
	v_mfma_f32_32x32x16_bf16 v[0:15], v[64:67], v[44:47], v[0:15]
	v_lshlrev_b32_e32 v16, 16, v242
	v_and_b32_e32 v17, 0xffff0000, v242
	v_lshlrev_b32_e32 v18, 16, v243
	v_and_b32_e32 v19, 0xffff0000, v243
	v_mul_f32_e32 v16, v20, v16
	v_mul_f32_e32 v17, v21, v17
	v_mul_f32_e32 v18, v22, v18
	v_mul_f32_e32 v19, v23, v19
	v_cvt_pk_bf16_f32 v16, v16, v17
	v_cvt_pk_bf16_f32 v17, v18, v19
	v_mul_f32_e32 v20, v68, v28
	v_mul_f32_e32 v21, v68, v29
	v_mul_f32_e32 v22, v68, v30
	v_mul_f32_e32 v23, v68, v31
	v_mov_b32_e32 v200, v16
	v_mov_b32_e32 v201, v17
	v_mul_f32_e32 v0, v68, v0
	v_mul_f32_e32 v1, v68, v1
	v_mul_f32_e32 v2, v68, v2
	v_mul_f32_e32 v3, v68, v3
	v_mul_f32_e32 v4, v68, v4
	v_mul_f32_e32 v5, v68, v5
	v_mul_f32_e32 v6, v68, v6
	v_mul_f32_e32 v7, v68, v7
	v_lshlrev_b32_e32 v16, 16, v244
	v_and_b32_e32 v17, 0xffff0000, v244
	v_lshlrev_b32_e32 v18, 16, v245
	v_and_b32_e32 v19, 0xffff0000, v245
	v_mul_f32_e32 v16, v20, v16
	v_mul_f32_e32 v17, v21, v17
	v_mul_f32_e32 v18, v22, v18
	v_mul_f32_e32 v19, v23, v19
	v_cvt_pk_bf16_f32 v16, v16, v17
	v_cvt_pk_bf16_f32 v17, v18, v19
	s_nop 0
	v_mov_b32_e32 v202, v16
	v_mov_b32_e32 v203, v17
	s_nop 1
	v_permlane32_swap_b32_e32 v200, v202
	v_permlane32_swap_b32_e32 v201, v203
	global_store_dwordx4 v[198:199], v[200:203], off offset:32
	v_lshlrev_b32_e32 v16, 16, v246
	v_and_b32_e32 v17, 0xffff0000, v246
	v_lshlrev_b32_e32 v18, 16, v247
	v_and_b32_e32 v19, 0xffff0000, v247
	v_mul_f32_e32 v0, v0, v16
	v_mul_f32_e32 v1, v1, v17
	v_mul_f32_e32 v2, v2, v18
	v_mul_f32_e32 v3, v3, v19
	v_cvt_pk_bf16_f32 v0, v0, v1
	v_cvt_pk_bf16_f32 v1, v2, v3
	s_nop 0
	v_mov_b32_e32 v200, v0
	v_mov_b32_e32 v201, v1
	v_lshlrev_b32_e32 v0, 16, v248
	v_and_b32_e32 v1, 0xffff0000, v248
	v_lshlrev_b32_e32 v2, 16, v249
	v_and_b32_e32 v3, 0xffff0000, v249
	v_mul_f32_e32 v0, v4, v0
	v_mul_f32_e32 v1, v5, v1
	v_mul_f32_e32 v2, v6, v2
	v_mul_f32_e32 v3, v7, v3
	v_cvt_pk_bf16_f32 v0, v0, v1
	v_cvt_pk_bf16_f32 v1, v2, v3
	v_mul_f32_e32 v4, v68, v8
	v_mul_f32_e32 v5, v68, v9
	v_mul_f32_e32 v6, v68, v10
	v_mul_f32_e32 v7, v68, v11
	v_mov_b32_e32 v202, v0
	v_mov_b32_e32 v203, v1
	s_nop 1
	v_permlane32_swap_b32_e32 v200, v202
	v_permlane32_swap_b32_e32 v201, v203
	global_store_dwordx4 v[198:199], v[200:203], off offset:64
	v_lshlrev_b32_e32 v0, 16, v250
	v_and_b32_e32 v1, 0xffff0000, v250
	v_lshlrev_b32_e32 v2, 16, v251
	v_and_b32_e32 v3, 0xffff0000, v251
	v_mul_f32_e32 v0, v4, v0
	v_mul_f32_e32 v1, v5, v1
	v_mul_f32_e32 v2, v6, v2
	v_mul_f32_e32 v3, v7, v3
	v_cvt_pk_bf16_f32 v0, v0, v1
	v_cvt_pk_bf16_f32 v1, v2, v3
	v_mul_f32_e32 v4, v68, v12
	v_mul_f32_e32 v5, v68, v13
	v_mov_b32_e32 v200, v0
	v_mov_b32_e32 v201, v1
	v_mul_f32_e32 v6, v68, v14
	v_mul_f32_e32 v7, v68, v15
	v_lshlrev_b32_e32 v0, 16, v252
	v_and_b32_e32 v1, 0xffff0000, v252
	v_lshlrev_b32_e32 v2, 16, v253
	v_and_b32_e32 v3, 0xffff0000, v253
	v_mul_f32_e32 v0, v4, v0
	v_mul_f32_e32 v1, v5, v1
	v_mul_f32_e32 v2, v6, v2
	v_mul_f32_e32 v3, v7, v3
	v_cvt_pk_bf16_f32 v0, v0, v1
	v_cvt_pk_bf16_f32 v1, v2, v3
	v_mov_b32_e32 v202, v0
	v_mov_b32_e32 v203, v1
	s_nop 1
	v_permlane32_swap_b32_e32 v200, v202
	v_permlane32_swap_b32_e32 v201, v203
	global_store_dwordx4 v[198:199], v[200:203], off offset:96
	s_barrier
